# P1 epilogue: the two hoisted next-unit LDS-DMA loads are issued after the q/k-norm and rotary variants' own table loads have been waited for (v/gates variant unchanged)
# baseline (speedup 1.0000x reference)
;     __device__ __forceinline__ void operator()(const f32x4 (&acc)[2][2][4][2], const pg8::Unit& u, int wr, int wc, int fr, int fq) const {
;         const int sec = u.pn >> 1, half = u.pn & 1;
;         bf16_t* base = proj + (size_t)sec * SEC_STRIDE;
;         const int row0 = u.pm * 256 + wr * 64 + fr;
;         if (sec <= 1) {
.LBB0_165:
	s_add_u32 s94, s34, 0x40080
	s_addc_u32 s95, s5, 0
	s_ashr_i32 s41, s46, 1
	s_and_b32 s27, s46, 1
	s_mul_i32 s34, s41, 0x5000000
	s_mul_hi_i32 s5, s41, 0x5000000
	s_add_u32 s48, s78, s34
	s_addc_u32 s49, s79, s5
	v_lshl_add_u32 v172, s4, 8, v1
	s_cmp_gt_i32 s41, 1
	s_mov_b64 s[4:5], -1
	s_cbranch_scc1 .LBB0_168
	s_andn2_b64 vcc, exec, s[4:5]
	s_cbranch_vccz .LBB0_205

; __device__ __forceinline__ unsigned cvt_pk_bf16(float lo, float hi) { unsigned r; asm volatile("v_cvt_pk_bf16_f32 %0, %1, %2" : "=v"(r) : "v"(lo), "v"(hi)); return r; }
; __device__ __forceinline__ float silu_f(float x) { return x * __builtin_amdgcn_rcpf(1.f + __expf(-x)); }
;     __device__ __forceinline__ void operator()(const f32x4 (&acc)[2][2][4][2], const pg8::Unit& u, int wr, int wc, int fr, int fq) const {
;     ...
;         } else {
;             const bool act = (sec == 3 || sec == 7);
;             const int col0 = 256 * half + 64 * wc + 8 * fq;
; #pragma unroll
;             for (int ai = 0; ai < 2; ++ai)
; #pragma unroll
;                 for (int m = 0; m < 4; ++m) {
;                     bf16_t* rowp = base + (size_t)(row0 + ai * 128 + m * 16) * 512 + col0;
; #pragma unroll
;                     for (int bj = 0; bj < 2; ++bj) { f32x4 v0 = acc[ai][bj][m][0], v1 = acc[ai][bj][m][1];
;                         if (act) { v0 = (f32x4){silu_f(v0[0]), silu_f(v0[1]), silu_f(v0[2]), silu_f(v0[3])}; v1 = (f32x4){silu_f(v1[0]), silu_f(v1[1]), silu_f(v1[2]), silu_f(v1[3])}; }
;                         u32x4 w; w.x = cvt_pk_bf16(v0[0], v0[1]); w.y = cvt_pk_bf16(v0[2], v0[3]); w.z = cvt_pk_bf16(v1[0], v1[1]); w.w = cvt_pk_bf16(v1[2], v1[3]);
;                         *(u32x4*)(rowp + 32 * bj) = w; }
;                 }
.LBB0_168:
	s_and_b32 s4, s41, 0x7ffffffe
	s_cmp_lg_u32 s4, 4
	s_mov_b64 s[4:5], -1
	s_cbranch_scc0 .LBB0_202
	s_add_i32 m0, s47, 0xc000
	s_nop 0
	global_load_lds_dwordx4 v164, s[94:95]
	s_add_i32 m0, s47, 0xe000
	s_nop 0
	global_load_lds_dwordx4 v166, s[94:95]
	s_and_b32 s4, s41, 0x7ffffffb
	v_lshlrev_b32_e32 v130, 1, v182
	v_lshl_or_b32 v154, s27, 9, v130
	v_and_b32_e32 v131, 1, v172
	v_lshl_add_u32 v154, v131, 6, v154
	v_and_b32_e32 v132, -2, v172
	v_ashrrev_i32_e32 v173, 31, v172
	v_ashrrev_i32_e32 v133, 31, v132
	v_lshlrev_b64 v[132:133], 10, v[132:133]
	v_lshl_add_u64 v[130:131], s[48:49], 0, v[154:155]
	v_lshl_add_u64 v[130:131], v[130:131], 0, v[132:133]
	s_mov_b32 vcc_lo, 0x55555555
	s_mov_b32 vcc_hi, 0x55555555
	s_cmp_lg_u32 s4, 3
	s_mov_b64 s[4:5], 0x4000
	s_cbranch_scc1 .Lp1e_plain
	v_mul_f32_e32 v224, 0xbfb8aa3b, v118
	v_mul_f32_e32 v225, 0xbfb8aa3b, v119
	v_mul_f32_e32 v226, 0xbfb8aa3b, v120
	v_mul_f32_e32 v227, 0xbfb8aa3b, v121
	v_mul_f32_e32 v228, 0xbfb8aa3b, v114
	v_mul_f32_e32 v229, 0xbfb8aa3b, v115
	v_mul_f32_e32 v230, 0xbfb8aa3b, v116
	v_mul_f32_e32 v231, 0xbfb8aa3b, v117
	v_exp_f32_e32 v224, v224
	v_exp_f32_e32 v225, v225
	v_exp_f32_e32 v226, v226
	v_exp_f32_e32 v227, v227
	v_exp_f32_e32 v228, v228
	v_exp_f32_e32 v229, v229
	v_exp_f32_e32 v230, v230
	v_exp_f32_e32 v231, v231
	v_add_f32_e32 v224, 1.0, v224
	v_add_f32_e32 v225, 1.0, v225
	v_add_f32_e32 v226, 1.0, v226
	v_add_f32_e32 v227, 1.0, v227
	v_add_f32_e32 v228, 1.0, v228
	v_add_f32_e32 v229, 1.0, v229
	v_add_f32_e32 v230, 1.0, v230
	v_add_f32_e32 v231, 1.0, v231
	v_rcp_f32_e32 v224, v224
	v_rcp_f32_e32 v225, v225
	v_rcp_f32_e32 v226, v226
	v_rcp_f32_e32 v227, v227
	v_rcp_f32_e32 v228, v228
	v_rcp_f32_e32 v229, v229
	v_rcp_f32_e32 v230, v230
	v_rcp_f32_e32 v231, v231
	v_pk_mul_f32 v[224:225], v[118:119], v[224:225]
	v_pk_mul_f32 v[226:227], v[120:121], v[226:227]
	v_pk_mul_f32 v[228:229], v[114:115], v[228:229]
	v_pk_mul_f32 v[230:231], v[116:117], v[230:231]
	v_cvt_pk_bf16_f32 v204, v224, v225
	v_cvt_pk_bf16_f32 v205, v226, v227
	v_cvt_pk_bf16_f32 v206, v228, v229
	v_cvt_pk_bf16_f32 v207, v230, v231
	v_mul_f32_e32 v132, 0xbfb8aa3b, v126
	v_mul_f32_e32 v133, 0xbfb8aa3b, v127
	v_mul_f32_e32 v134, 0xbfb8aa3b, v128
	v_mul_f32_e32 v135, 0xbfb8aa3b, v129
	v_mul_f32_e32 v136, 0xbfb8aa3b, v122
	v_mul_f32_e32 v137, 0xbfb8aa3b, v123
	v_mul_f32_e32 v138, 0xbfb8aa3b, v124
	v_mul_f32_e32 v139, 0xbfb8aa3b, v125
	v_exp_f32_e32 v132, v132
	v_exp_f32_e32 v133, v133
	v_exp_f32_e32 v134, v134
	v_exp_f32_e32 v135, v135
	v_exp_f32_e32 v136, v136
	v_exp_f32_e32 v137, v137
	v_exp_f32_e32 v138, v138
	v_exp_f32_e32 v139, v139
	v_add_f32_e32 v132, 1.0, v132
	v_add_f32_e32 v133, 1.0, v133
	v_add_f32_e32 v134, 1.0, v134
	v_add_f32_e32 v135, 1.0, v135
	v_add_f32_e32 v136, 1.0, v136
	v_add_f32_e32 v137, 1.0, v137
	v_add_f32_e32 v138, 1.0, v138
	v_add_f32_e32 v139, 1.0, v139
	v_rcp_f32_e32 v132, v132
	v_rcp_f32_e32 v133, v133
	v_rcp_f32_e32 v134, v134
	v_rcp_f32_e32 v135, v135
	v_rcp_f32_e32 v136, v136
	v_rcp_f32_e32 v137, v137
	v_rcp_f32_e32 v138, v138
	v_rcp_f32_e32 v139, v139
	v_pk_mul_f32 v[132:133], v[126:127], v[132:133]
	v_pk_mul_f32 v[134:135], v[128:129], v[134:135]
	v_pk_mul_f32 v[136:137], v[122:123], v[136:137]
	v_pk_mul_f32 v[138:139], v[124:125], v[138:139]
	v_cvt_pk_bf16_f32 v200, v132, v133
	v_cvt_pk_bf16_f32 v201, v134, v135
	v_cvt_pk_bf16_f32 v202, v136, v137
	v_cvt_pk_bf16_f32 v203, v138, v139
	v_cndmask_b32_dpp v208, v204, v200, vcc quad_perm:[1,0,3,2] row_mask:0xf bank_mask:0xf
	v_cndmask_b32_dpp v209, v205, v201, vcc quad_perm:[1,0,3,2] row_mask:0xf bank_mask:0xf
	v_cndmask_b32_dpp v210, v206, v202, vcc quad_perm:[1,0,3,2] row_mask:0xf bank_mask:0xf
	v_cndmask_b32_dpp v211, v207, v203, vcc quad_perm:[1,0,3,2] row_mask:0xf bank_mask:0xf
	s_not_b64 vcc, vcc
	v_cndmask_b32_dpp v212, v200, v204, vcc quad_perm:[1,0,3,2] row_mask:0xf bank_mask:0xf
	v_cndmask_b32_dpp v213, v201, v205, vcc quad_perm:[1,0,3,2] row_mask:0xf bank_mask:0xf
	v_cndmask_b32_dpp v214, v202, v206, vcc quad_perm:[1,0,3,2] row_mask:0xf bank_mask:0xf
	v_cndmask_b32_dpp v215, v203, v207, vcc quad_perm:[1,0,3,2] row_mask:0xf bank_mask:0xf
	s_not_b64 vcc, vcc
	global_store_dwordx4 v[130:131], v[208:211], off
	global_store_dwordx4 v[130:131], v[212:215], off offset:1024
	v_lshl_add_u64 v[130:131], v[130:131], 0, s[4:5]
	v_mul_f32_e32 v224, 0xbfb8aa3b, v102
	v_mul_f32_e32 v225, 0xbfb8aa3b, v103
	v_mul_f32_e32 v226, 0xbfb8aa3b, v104
	v_mul_f32_e32 v227, 0xbfb8aa3b, v105
	v_mul_f32_e32 v228, 0xbfb8aa3b, v98
	v_mul_f32_e32 v229, 0xbfb8aa3b, v99
	v_mul_f32_e32 v230, 0xbfb8aa3b, v100
	v_mul_f32_e32 v231, 0xbfb8aa3b, v101
	v_exp_f32_e32 v224, v224
	v_exp_f32_e32 v225, v225
	v_exp_f32_e32 v226, v226
	v_exp_f32_e32 v227, v227
	v_exp_f32_e32 v228, v228
	v_exp_f32_e32 v229, v229
	v_exp_f32_e32 v230, v230
	v_exp_f32_e32 v231, v231
	v_add_f32_e32 v224, 1.0, v224
	v_add_f32_e32 v225, 1.0, v225
	v_add_f32_e32 v226, 1.0, v226
	v_add_f32_e32 v227, 1.0, v227
	v_add_f32_e32 v228, 1.0, v228
	v_add_f32_e32 v229, 1.0, v229
	v_add_f32_e32 v230, 1.0, v230
	v_add_f32_e32 v231, 1.0, v231
	v_rcp_f32_e32 v224, v224
	v_rcp_f32_e32 v225, v225
	v_rcp_f32_e32 v226, v226
	v_rcp_f32_e32 v227, v227
	v_rcp_f32_e32 v228, v228
	v_rcp_f32_e32 v229, v229
	v_rcp_f32_e32 v230, v230
	v_rcp_f32_e32 v231, v231
	v_pk_mul_f32 v[224:225], v[102:103], v[224:225]
	v_pk_mul_f32 v[226:227], v[104:105], v[226:227]
	v_pk_mul_f32 v[228:229], v[98:99], v[228:229]
	v_pk_mul_f32 v[230:231], v[100:101], v[230:231]
	v_cvt_pk_bf16_f32 v204, v224, v225
	v_cvt_pk_bf16_f32 v205, v226, v227
	v_cvt_pk_bf16_f32 v206, v228, v229
	v_cvt_pk_bf16_f32 v207, v230, v231
; __device__ __forceinline__ unsigned cvt_pk_bf16(float lo, float hi) { unsigned r; asm volatile("v_cvt_pk_bf16_f32 %0, %1, %2" : "=v"(r) : "v"(lo), "v"(hi)); return r; }
; __device__ __forceinline__ float silu_f(float x) { return x * __builtin_amdgcn_rcpf(1.f + __expf(-x)); }
;     __device__ __forceinline__ void operator()(const f32x4 (&acc)[2][2][4][2], const pg8::Unit& u, int wr, int wc, int fr, int fq) const {
;     ...
;                     bf16_t* rowp = base + (size_t)(row0 + ai * 128 + m * 16) * 512 + col0;
; #pragma unroll
;                     for (int bj = 0; bj < 2; ++bj) { f32x4 v0 = acc[ai][bj][m][0], v1 = acc[ai][bj][m][1];
;                         if (act) { v0 = (f32x4){silu_f(v0[0]), silu_f(v0[1]), silu_f(v0[2]), silu_f(v0[3])}; v1 = (f32x4){silu_f(v1[0]), silu_f(v1[1]), silu_f(v1[2]), silu_f(v1[3])}; }
;                         u32x4 w; w.x = cvt_pk_bf16(v0[0], v0[1]); w.y = cvt_pk_bf16(v0[2], v0[3]); w.z = cvt_pk_bf16(v1[0], v1[1]); w.w = cvt_pk_bf16(v1[2], v1[3]);
;                         *(u32x4*)(rowp + 32 * bj) = w; }
	v_mul_f32_e32 v132, 0xbfb8aa3b, v110
	v_mul_f32_e32 v133, 0xbfb8aa3b, v111
	v_mul_f32_e32 v134, 0xbfb8aa3b, v112
	v_mul_f32_e32 v135, 0xbfb8aa3b, v113
	v_mul_f32_e32 v136, 0xbfb8aa3b, v106
	v_mul_f32_e32 v137, 0xbfb8aa3b, v107
	v_mul_f32_e32 v138, 0xbfb8aa3b, v108
	v_mul_f32_e32 v139, 0xbfb8aa3b, v109
	v_exp_f32_e32 v132, v132
	v_exp_f32_e32 v133, v133
	v_exp_f32_e32 v134, v134
	v_exp_f32_e32 v135, v135
	v_exp_f32_e32 v136, v136
	v_exp_f32_e32 v137, v137
	v_exp_f32_e32 v138, v138
	v_exp_f32_e32 v139, v139
	v_add_f32_e32 v132, 1.0, v132
	v_add_f32_e32 v133, 1.0, v133
	v_add_f32_e32 v134, 1.0, v134
	v_add_f32_e32 v135, 1.0, v135
	v_add_f32_e32 v136, 1.0, v136
	v_add_f32_e32 v137, 1.0, v137
	v_add_f32_e32 v138, 1.0, v138
	v_add_f32_e32 v139, 1.0, v139
	v_rcp_f32_e32 v132, v132
	v_rcp_f32_e32 v133, v133
	v_rcp_f32_e32 v134, v134
	v_rcp_f32_e32 v135, v135
	v_rcp_f32_e32 v136, v136
	v_rcp_f32_e32 v137, v137
	v_rcp_f32_e32 v138, v138
	v_rcp_f32_e32 v139, v139
	v_pk_mul_f32 v[132:133], v[110:111], v[132:133]
	v_pk_mul_f32 v[134:135], v[112:113], v[134:135]
	v_pk_mul_f32 v[136:137], v[106:107], v[136:137]
	v_pk_mul_f32 v[138:139], v[108:109], v[138:139]
	v_cvt_pk_bf16_f32 v200, v132, v133
	v_cvt_pk_bf16_f32 v201, v134, v135
	v_cvt_pk_bf16_f32 v202, v136, v137
	v_cvt_pk_bf16_f32 v203, v138, v139
	v_cndmask_b32_dpp v216, v204, v200, vcc quad_perm:[1,0,3,2] row_mask:0xf bank_mask:0xf
	v_cndmask_b32_dpp v217, v205, v201, vcc quad_perm:[1,0,3,2] row_mask:0xf bank_mask:0xf
	v_cndmask_b32_dpp v218, v206, v202, vcc quad_perm:[1,0,3,2] row_mask:0xf bank_mask:0xf
	v_cndmask_b32_dpp v219, v207, v203, vcc quad_perm:[1,0,3,2] row_mask:0xf bank_mask:0xf
	s_not_b64 vcc, vcc
	v_cndmask_b32_dpp v220, v200, v204, vcc quad_perm:[1,0,3,2] row_mask:0xf bank_mask:0xf
	v_cndmask_b32_dpp v221, v201, v205, vcc quad_perm:[1,0,3,2] row_mask:0xf bank_mask:0xf
	v_cndmask_b32_dpp v222, v202, v206, vcc quad_perm:[1,0,3,2] row_mask:0xf bank_mask:0xf
	v_cndmask_b32_dpp v223, v203, v207, vcc quad_perm:[1,0,3,2] row_mask:0xf bank_mask:0xf
	s_not_b64 vcc, vcc
	global_store_dwordx4 v[130:131], v[216:219], off
	global_store_dwordx4 v[130:131], v[220:223], off offset:1024
	v_lshl_add_u64 v[130:131], v[130:131], 0, s[4:5]
	v_mul_f32_e32 v224, 0xbfb8aa3b, v86
	v_mul_f32_e32 v225, 0xbfb8aa3b, v87
	v_mul_f32_e32 v226, 0xbfb8aa3b, v88
	v_mul_f32_e32 v227, 0xbfb8aa3b, v89
	v_mul_f32_e32 v228, 0xbfb8aa3b, v82
	v_mul_f32_e32 v229, 0xbfb8aa3b, v83
	v_mul_f32_e32 v230, 0xbfb8aa3b, v84
	v_mul_f32_e32 v231, 0xbfb8aa3b, v85
	v_exp_f32_e32 v224, v224
	v_exp_f32_e32 v225, v225
	v_exp_f32_e32 v226, v226
	v_exp_f32_e32 v227, v227
	v_exp_f32_e32 v228, v228
	v_exp_f32_e32 v229, v229
	v_exp_f32_e32 v230, v230
	v_exp_f32_e32 v231, v231
	v_add_f32_e32 v224, 1.0, v224
	v_add_f32_e32 v225, 1.0, v225
	v_add_f32_e32 v226, 1.0, v226
	v_add_f32_e32 v227, 1.0, v227
	v_add_f32_e32 v228, 1.0, v228
	v_add_f32_e32 v229, 1.0, v229
	v_add_f32_e32 v230, 1.0, v230
	v_add_f32_e32 v231, 1.0, v231
	v_rcp_f32_e32 v224, v224
	v_rcp_f32_e32 v225, v225
	v_rcp_f32_e32 v226, v226
	v_rcp_f32_e32 v227, v227
	v_rcp_f32_e32 v228, v228
	v_rcp_f32_e32 v229, v229
	v_rcp_f32_e32 v230, v230
	v_rcp_f32_e32 v231, v231
	v_pk_mul_f32 v[224:225], v[86:87], v[224:225]
	v_pk_mul_f32 v[226:227], v[88:89], v[226:227]
	v_pk_mul_f32 v[228:229], v[82:83], v[228:229]
	v_pk_mul_f32 v[230:231], v[84:85], v[230:231]
	v_cvt_pk_bf16_f32 v204, v224, v225
	v_cvt_pk_bf16_f32 v205, v226, v227
	v_cvt_pk_bf16_f32 v206, v228, v229
	v_cvt_pk_bf16_f32 v207, v230, v231
	v_mul_f32_e32 v132, 0xbfb8aa3b, v94
	v_mul_f32_e32 v133, 0xbfb8aa3b, v95
	v_mul_f32_e32 v134, 0xbfb8aa3b, v96
	v_mul_f32_e32 v135, 0xbfb8aa3b, v97
	v_mul_f32_e32 v136, 0xbfb8aa3b, v90
	v_mul_f32_e32 v137, 0xbfb8aa3b, v91
	v_mul_f32_e32 v138, 0xbfb8aa3b, v92
	v_mul_f32_e32 v139, 0xbfb8aa3b, v93
	v_exp_f32_e32 v132, v132
	v_exp_f32_e32 v133, v133
	v_exp_f32_e32 v134, v134
	v_exp_f32_e32 v135, v135
	v_exp_f32_e32 v136, v136
	v_exp_f32_e32 v137, v137
	v_exp_f32_e32 v138, v138
	v_exp_f32_e32 v139, v139
	v_add_f32_e32 v132, 1.0, v132
	v_add_f32_e32 v133, 1.0, v133
	v_add_f32_e32 v134, 1.0, v134
	v_add_f32_e32 v135, 1.0, v135
	v_add_f32_e32 v136, 1.0, v136
	v_add_f32_e32 v137, 1.0, v137
	v_add_f32_e32 v138, 1.0, v138
	v_add_f32_e32 v139, 1.0, v139
	v_rcp_f32_e32 v132, v132
	v_rcp_f32_e32 v133, v133
	v_rcp_f32_e32 v134, v134
	v_rcp_f32_e32 v135, v135
	v_rcp_f32_e32 v136, v136
	v_rcp_f32_e32 v137, v137
	v_rcp_f32_e32 v138, v138
	v_rcp_f32_e32 v139, v139
	v_pk_mul_f32 v[132:133], v[94:95], v[132:133]
	v_pk_mul_f32 v[134:135], v[96:97], v[134:135]
	v_pk_mul_f32 v[136:137], v[90:91], v[136:137]
	v_pk_mul_f32 v[138:139], v[92:93], v[138:139]
	v_cvt_pk_bf16_f32 v200, v132, v133
	v_cvt_pk_bf16_f32 v201, v134, v135
	v_cvt_pk_bf16_f32 v202, v136, v137
	v_cvt_pk_bf16_f32 v203, v138, v139
	v_cndmask_b32_dpp v208, v204, v200, vcc quad_perm:[1,0,3,2] row_mask:0xf bank_mask:0xf
	v_cndmask_b32_dpp v209, v205, v201, vcc quad_perm:[1,0,3,2] row_mask:0xf bank_mask:0xf
	v_cndmask_b32_dpp v210, v206, v202, vcc quad_perm:[1,0,3,2] row_mask:0xf bank_mask:0xf
	v_cndmask_b32_dpp v211, v207, v203, vcc quad_perm:[1,0,3,2] row_mask:0xf bank_mask:0xf
	s_not_b64 vcc, vcc
	v_cndmask_b32_dpp v212, v200, v204, vcc quad_perm:[1,0,3,2] row_mask:0xf bank_mask:0xf
	v_cndmask_b32_dpp v213, v201, v205, vcc quad_perm:[1,0,3,2] row_mask:0xf bank_mask:0xf
	v_cndmask_b32_dpp v214, v202, v206, vcc quad_perm:[1,0,3,2] row_mask:0xf bank_mask:0xf
	v_cndmask_b32_dpp v215, v203, v207, vcc quad_perm:[1,0,3,2] row_mask:0xf bank_mask:0xf
	s_not_b64 vcc, vcc
	global_store_dwordx4 v[130:131], v[208:211], off
	global_store_dwordx4 v[130:131], v[212:215], off offset:1024
; __device__ __forceinline__ unsigned cvt_pk_bf16(float lo, float hi) { unsigned r; asm volatile("v_cvt_pk_bf16_f32 %0, %1, %2" : "=v"(r) : "v"(lo), "v"(hi)); return r; }
; __device__ __forceinline__ float silu_f(float x) { return x * __builtin_amdgcn_rcpf(1.f + __expf(-x)); }
;     __device__ __forceinline__ void operator()(const f32x4 (&acc)[2][2][4][2], const pg8::Unit& u, int wr, int wc, int fr, int fq) const {
;     ...
;                     bf16_t* rowp = base + (size_t)(row0 + ai * 128 + m * 16) * 512 + col0;
; #pragma unroll
;                     for (int bj = 0; bj < 2; ++bj) { f32x4 v0 = acc[ai][bj][m][0], v1 = acc[ai][bj][m][1];
;                         if (act) { v0 = (f32x4){silu_f(v0[0]), silu_f(v0[1]), silu_f(v0[2]), silu_f(v0[3])}; v1 = (f32x4){silu_f(v1[0]), silu_f(v1[1]), silu_f(v1[2]), silu_f(v1[3])}; }
;                         u32x4 w; w.x = cvt_pk_bf16(v0[0], v0[1]); w.y = cvt_pk_bf16(v0[2], v0[3]); w.z = cvt_pk_bf16(v1[0], v1[1]); w.w = cvt_pk_bf16(v1[2], v1[3]);
;                         *(u32x4*)(rowp + 32 * bj) = w; }
	v_lshl_add_u64 v[130:131], v[130:131], 0, s[4:5]
	v_mul_f32_e32 v224, 0xbfb8aa3b, v70
	v_mul_f32_e32 v225, 0xbfb8aa3b, v71
	v_mul_f32_e32 v226, 0xbfb8aa3b, v72
	v_mul_f32_e32 v227, 0xbfb8aa3b, v73
	v_mul_f32_e32 v228, 0xbfb8aa3b, v66
	v_mul_f32_e32 v229, 0xbfb8aa3b, v67
	v_mul_f32_e32 v230, 0xbfb8aa3b, v68
	v_mul_f32_e32 v231, 0xbfb8aa3b, v69
	v_exp_f32_e32 v224, v224
	v_exp_f32_e32 v225, v225
	v_exp_f32_e32 v226, v226
	v_exp_f32_e32 v227, v227
	v_exp_f32_e32 v228, v228
	v_exp_f32_e32 v229, v229
	v_exp_f32_e32 v230, v230
	v_exp_f32_e32 v231, v231
	v_add_f32_e32 v224, 1.0, v224
	v_add_f32_e32 v225, 1.0, v225
	v_add_f32_e32 v226, 1.0, v226
	v_add_f32_e32 v227, 1.0, v227
	v_add_f32_e32 v228, 1.0, v228
	v_add_f32_e32 v229, 1.0, v229
	v_add_f32_e32 v230, 1.0, v230
	v_add_f32_e32 v231, 1.0, v231
	v_rcp_f32_e32 v224, v224
	v_rcp_f32_e32 v225, v225
	v_rcp_f32_e32 v226, v226
	v_rcp_f32_e32 v227, v227
	v_rcp_f32_e32 v228, v228
	v_rcp_f32_e32 v229, v229
	v_rcp_f32_e32 v230, v230
	v_rcp_f32_e32 v231, v231
	v_pk_mul_f32 v[224:225], v[70:71], v[224:225]
	v_pk_mul_f32 v[226:227], v[72:73], v[226:227]
	v_pk_mul_f32 v[228:229], v[66:67], v[228:229]
	v_pk_mul_f32 v[230:231], v[68:69], v[230:231]
	v_cvt_pk_bf16_f32 v204, v224, v225
	v_cvt_pk_bf16_f32 v205, v226, v227
	v_cvt_pk_bf16_f32 v206, v228, v229
	v_cvt_pk_bf16_f32 v207, v230, v231
	v_mul_f32_e32 v132, 0xbfb8aa3b, v78
	v_mul_f32_e32 v133, 0xbfb8aa3b, v79
	v_mul_f32_e32 v134, 0xbfb8aa3b, v80
	v_mul_f32_e32 v135, 0xbfb8aa3b, v81
	v_mul_f32_e32 v136, 0xbfb8aa3b, v74
	v_mul_f32_e32 v137, 0xbfb8aa3b, v75
	v_mul_f32_e32 v138, 0xbfb8aa3b, v76
	v_mul_f32_e32 v139, 0xbfb8aa3b, v77
	v_exp_f32_e32 v132, v132
	v_exp_f32_e32 v133, v133
	v_exp_f32_e32 v134, v134
	v_exp_f32_e32 v135, v135
	v_exp_f32_e32 v136, v136
	v_exp_f32_e32 v137, v137
	v_exp_f32_e32 v138, v138
	v_exp_f32_e32 v139, v139
	v_add_f32_e32 v132, 1.0, v132
	v_add_f32_e32 v133, 1.0, v133
	v_add_f32_e32 v134, 1.0, v134
	v_add_f32_e32 v135, 1.0, v135
	v_add_f32_e32 v136, 1.0, v136
	v_add_f32_e32 v137, 1.0, v137
	v_add_f32_e32 v138, 1.0, v138
	v_add_f32_e32 v139, 1.0, v139
	v_rcp_f32_e32 v132, v132
	v_rcp_f32_e32 v133, v133
	v_rcp_f32_e32 v134, v134
	v_rcp_f32_e32 v135, v135
	v_rcp_f32_e32 v136, v136
	v_rcp_f32_e32 v137, v137
	v_rcp_f32_e32 v138, v138
	v_rcp_f32_e32 v139, v139
	v_pk_mul_f32 v[132:133], v[78:79], v[132:133]
	v_pk_mul_f32 v[134:135], v[80:81], v[134:135]
	v_pk_mul_f32 v[136:137], v[74:75], v[136:137]
	v_pk_mul_f32 v[138:139], v[76:77], v[138:139]
	v_cvt_pk_bf16_f32 v200, v132, v133
	v_cvt_pk_bf16_f32 v201, v134, v135
	v_cvt_pk_bf16_f32 v202, v136, v137
	v_cvt_pk_bf16_f32 v203, v138, v139
	v_cndmask_b32_dpp v216, v204, v200, vcc quad_perm:[1,0,3,2] row_mask:0xf bank_mask:0xf
	v_cndmask_b32_dpp v217, v205, v201, vcc quad_perm:[1,0,3,2] row_mask:0xf bank_mask:0xf
	v_cndmask_b32_dpp v218, v206, v202, vcc quad_perm:[1,0,3,2] row_mask:0xf bank_mask:0xf
	v_cndmask_b32_dpp v219, v207, v203, vcc quad_perm:[1,0,3,2] row_mask:0xf bank_mask:0xf
	s_not_b64 vcc, vcc
	v_cndmask_b32_dpp v220, v200, v204, vcc quad_perm:[1,0,3,2] row_mask:0xf bank_mask:0xf
	v_cndmask_b32_dpp v221, v201, v205, vcc quad_perm:[1,0,3,2] row_mask:0xf bank_mask:0xf
	v_cndmask_b32_dpp v222, v202, v206, vcc quad_perm:[1,0,3,2] row_mask:0xf bank_mask:0xf
	v_cndmask_b32_dpp v223, v203, v207, vcc quad_perm:[1,0,3,2] row_mask:0xf bank_mask:0xf
	s_not_b64 vcc, vcc
	global_store_dwordx4 v[130:131], v[216:219], off
	global_store_dwordx4 v[130:131], v[220:223], off offset:1024
	s_mov_b64 s[4:5], 0x14000
	v_lshl_add_u64 v[130:131], v[130:131], 0, s[4:5]
	s_mov_b64 s[4:5], 0x4000
	v_mul_f32_e32 v224, 0xbfb8aa3b, v54
	v_mul_f32_e32 v225, 0xbfb8aa3b, v55
	v_mul_f32_e32 v226, 0xbfb8aa3b, v56
	v_mul_f32_e32 v227, 0xbfb8aa3b, v57
	v_mul_f32_e32 v228, 0xbfb8aa3b, v50
	v_mul_f32_e32 v229, 0xbfb8aa3b, v51
	v_mul_f32_e32 v230, 0xbfb8aa3b, v52
	v_mul_f32_e32 v231, 0xbfb8aa3b, v53
	v_exp_f32_e32 v224, v224
	v_exp_f32_e32 v225, v225
	v_exp_f32_e32 v226, v226
	v_exp_f32_e32 v227, v227
	v_exp_f32_e32 v228, v228
	v_exp_f32_e32 v229, v229
	v_exp_f32_e32 v230, v230
	v_exp_f32_e32 v231, v231
	v_add_f32_e32 v224, 1.0, v224
	v_add_f32_e32 v225, 1.0, v225
	v_add_f32_e32 v226, 1.0, v226
	v_add_f32_e32 v227, 1.0, v227
	v_add_f32_e32 v228, 1.0, v228
	v_add_f32_e32 v229, 1.0, v229
	v_add_f32_e32 v230, 1.0, v230
	v_add_f32_e32 v231, 1.0, v231
	v_rcp_f32_e32 v224, v224
	v_rcp_f32_e32 v225, v225
	v_rcp_f32_e32 v226, v226
	v_rcp_f32_e32 v227, v227
	v_rcp_f32_e32 v228, v228
	v_rcp_f32_e32 v229, v229
	v_rcp_f32_e32 v230, v230
	v_rcp_f32_e32 v231, v231
	v_pk_mul_f32 v[224:225], v[54:55], v[224:225]
	v_pk_mul_f32 v[226:227], v[56:57], v[226:227]
	v_pk_mul_f32 v[228:229], v[50:51], v[228:229]
	v_pk_mul_f32 v[230:231], v[52:53], v[230:231]
	v_cvt_pk_bf16_f32 v204, v224, v225
	v_cvt_pk_bf16_f32 v205, v226, v227
	v_cvt_pk_bf16_f32 v206, v228, v229
	v_cvt_pk_bf16_f32 v207, v230, v231
	v_mul_f32_e32 v132, 0xbfb8aa3b, v62
	v_mul_f32_e32 v133, 0xbfb8aa3b, v63
	v_mul_f32_e32 v134, 0xbfb8aa3b, v64
	v_mul_f32_e32 v135, 0xbfb8aa3b, v65
	v_mul_f32_e32 v136, 0xbfb8aa3b, v58
	v_mul_f32_e32 v137, 0xbfb8aa3b, v59
	v_mul_f32_e32 v138, 0xbfb8aa3b, v60
	v_mul_f32_e32 v139, 0xbfb8aa3b, v61
	v_exp_f32_e32 v132, v132
	v_exp_f32_e32 v133, v133
	v_exp_f32_e32 v134, v134
	v_exp_f32_e32 v135, v135
	v_exp_f32_e32 v136, v136
	v_exp_f32_e32 v137, v137
	v_exp_f32_e32 v138, v138
	v_exp_f32_e32 v139, v139
	v_add_f32_e32 v132, 1.0, v132
	v_add_f32_e32 v133, 1.0, v133
	v_add_f32_e32 v134, 1.0, v134
	v_add_f32_e32 v135, 1.0, v135
	v_add_f32_e32 v136, 1.0, v136
	v_add_f32_e32 v137, 1.0, v137
	v_add_f32_e32 v138, 1.0, v138
	v_add_f32_e32 v139, 1.0, v139
; __device__ __forceinline__ unsigned cvt_pk_bf16(float lo, float hi) { unsigned r; asm volatile("v_cvt_pk_bf16_f32 %0, %1, %2" : "=v"(r) : "v"(lo), "v"(hi)); return r; }
; __device__ __forceinline__ float silu_f(float x) { return x * __builtin_amdgcn_rcpf(1.f + __expf(-x)); }
;     __device__ __forceinline__ void operator()(const f32x4 (&acc)[2][2][4][2], const pg8::Unit& u, int wr, int wc, int fr, int fq) const {
;     ...
;                     bf16_t* rowp = base + (size_t)(row0 + ai * 128 + m * 16) * 512 + col0;
; #pragma unroll
;                     for (int bj = 0; bj < 2; ++bj) { f32x4 v0 = acc[ai][bj][m][0], v1 = acc[ai][bj][m][1];
;                         if (act) { v0 = (f32x4){silu_f(v0[0]), silu_f(v0[1]), silu_f(v0[2]), silu_f(v0[3])}; v1 = (f32x4){silu_f(v1[0]), silu_f(v1[1]), silu_f(v1[2]), silu_f(v1[3])}; }
;                         u32x4 w; w.x = cvt_pk_bf16(v0[0], v0[1]); w.y = cvt_pk_bf16(v0[2], v0[3]); w.z = cvt_pk_bf16(v1[0], v1[1]); w.w = cvt_pk_bf16(v1[2], v1[3]);
;                         *(u32x4*)(rowp + 32 * bj) = w; }
	v_rcp_f32_e32 v132, v132
	v_rcp_f32_e32 v133, v133
	v_rcp_f32_e32 v134, v134
	v_rcp_f32_e32 v135, v135
	v_rcp_f32_e32 v136, v136
	v_rcp_f32_e32 v137, v137
	v_rcp_f32_e32 v138, v138
	v_rcp_f32_e32 v139, v139
	v_pk_mul_f32 v[132:133], v[62:63], v[132:133]
	v_pk_mul_f32 v[134:135], v[64:65], v[134:135]
	v_pk_mul_f32 v[136:137], v[58:59], v[136:137]
	v_pk_mul_f32 v[138:139], v[60:61], v[138:139]
	v_cvt_pk_bf16_f32 v200, v132, v133
	v_cvt_pk_bf16_f32 v201, v134, v135
	v_cvt_pk_bf16_f32 v202, v136, v137
	v_cvt_pk_bf16_f32 v203, v138, v139
	v_cndmask_b32_dpp v208, v204, v200, vcc quad_perm:[1,0,3,2] row_mask:0xf bank_mask:0xf
	v_cndmask_b32_dpp v209, v205, v201, vcc quad_perm:[1,0,3,2] row_mask:0xf bank_mask:0xf
	v_cndmask_b32_dpp v210, v206, v202, vcc quad_perm:[1,0,3,2] row_mask:0xf bank_mask:0xf
	v_cndmask_b32_dpp v211, v207, v203, vcc quad_perm:[1,0,3,2] row_mask:0xf bank_mask:0xf
	s_not_b64 vcc, vcc
	v_cndmask_b32_dpp v212, v200, v204, vcc quad_perm:[1,0,3,2] row_mask:0xf bank_mask:0xf
	v_cndmask_b32_dpp v213, v201, v205, vcc quad_perm:[1,0,3,2] row_mask:0xf bank_mask:0xf
	v_cndmask_b32_dpp v214, v202, v206, vcc quad_perm:[1,0,3,2] row_mask:0xf bank_mask:0xf
	v_cndmask_b32_dpp v215, v203, v207, vcc quad_perm:[1,0,3,2] row_mask:0xf bank_mask:0xf
	s_not_b64 vcc, vcc
	global_store_dwordx4 v[130:131], v[208:211], off
	global_store_dwordx4 v[130:131], v[212:215], off offset:1024
	v_lshl_add_u64 v[130:131], v[130:131], 0, s[4:5]
	v_mul_f32_e32 v224, 0xbfb8aa3b, v38
	v_mul_f32_e32 v225, 0xbfb8aa3b, v39
	v_mul_f32_e32 v226, 0xbfb8aa3b, v40
	v_mul_f32_e32 v227, 0xbfb8aa3b, v41
	v_mul_f32_e32 v228, 0xbfb8aa3b, v34
	v_mul_f32_e32 v229, 0xbfb8aa3b, v35
	v_mul_f32_e32 v230, 0xbfb8aa3b, v36
	v_mul_f32_e32 v231, 0xbfb8aa3b, v37
	v_exp_f32_e32 v224, v224
	v_exp_f32_e32 v225, v225
	v_exp_f32_e32 v226, v226
	v_exp_f32_e32 v227, v227
	v_exp_f32_e32 v228, v228
	v_exp_f32_e32 v229, v229
	v_exp_f32_e32 v230, v230
	v_exp_f32_e32 v231, v231
	v_add_f32_e32 v224, 1.0, v224
	v_add_f32_e32 v225, 1.0, v225
	v_add_f32_e32 v226, 1.0, v226
	v_add_f32_e32 v227, 1.0, v227
	v_add_f32_e32 v228, 1.0, v228
	v_add_f32_e32 v229, 1.0, v229
	v_add_f32_e32 v230, 1.0, v230
	v_add_f32_e32 v231, 1.0, v231
	v_rcp_f32_e32 v224, v224
	v_rcp_f32_e32 v225, v225
	v_rcp_f32_e32 v226, v226
	v_rcp_f32_e32 v227, v227
	v_rcp_f32_e32 v228, v228
	v_rcp_f32_e32 v229, v229
	v_rcp_f32_e32 v230, v230
	v_rcp_f32_e32 v231, v231
	v_pk_mul_f32 v[224:225], v[38:39], v[224:225]
	v_pk_mul_f32 v[226:227], v[40:41], v[226:227]
	v_pk_mul_f32 v[228:229], v[34:35], v[228:229]
	v_pk_mul_f32 v[230:231], v[36:37], v[230:231]
	v_cvt_pk_bf16_f32 v204, v224, v225
	v_cvt_pk_bf16_f32 v205, v226, v227
	v_cvt_pk_bf16_f32 v206, v228, v229
	v_cvt_pk_bf16_f32 v207, v230, v231
	v_mul_f32_e32 v132, 0xbfb8aa3b, v46
	v_mul_f32_e32 v133, 0xbfb8aa3b, v47
	v_mul_f32_e32 v134, 0xbfb8aa3b, v48
	v_mul_f32_e32 v135, 0xbfb8aa3b, v49
	v_mul_f32_e32 v136, 0xbfb8aa3b, v42
	v_mul_f32_e32 v137, 0xbfb8aa3b, v43
	v_mul_f32_e32 v138, 0xbfb8aa3b, v44
	v_mul_f32_e32 v139, 0xbfb8aa3b, v45
	v_exp_f32_e32 v132, v132
	v_exp_f32_e32 v133, v133
	v_exp_f32_e32 v134, v134
	v_exp_f32_e32 v135, v135
	v_exp_f32_e32 v136, v136
	v_exp_f32_e32 v137, v137
	v_exp_f32_e32 v138, v138
	v_exp_f32_e32 v139, v139
	v_add_f32_e32 v132, 1.0, v132
	v_add_f32_e32 v133, 1.0, v133
	v_add_f32_e32 v134, 1.0, v134
	v_add_f32_e32 v135, 1.0, v135
	v_add_f32_e32 v136, 1.0, v136
	v_add_f32_e32 v137, 1.0, v137
	v_add_f32_e32 v138, 1.0, v138
	v_add_f32_e32 v139, 1.0, v139
	v_rcp_f32_e32 v132, v132
	v_rcp_f32_e32 v133, v133
	v_rcp_f32_e32 v134, v134
	v_rcp_f32_e32 v135, v135
	v_rcp_f32_e32 v136, v136
	v_rcp_f32_e32 v137, v137
	v_rcp_f32_e32 v138, v138
	v_rcp_f32_e32 v139, v139
	v_pk_mul_f32 v[132:133], v[46:47], v[132:133]
	v_pk_mul_f32 v[134:135], v[48:49], v[134:135]
	v_pk_mul_f32 v[136:137], v[42:43], v[136:137]
	v_pk_mul_f32 v[138:139], v[44:45], v[138:139]
	v_cvt_pk_bf16_f32 v200, v132, v133
	v_cvt_pk_bf16_f32 v201, v134, v135
	v_cvt_pk_bf16_f32 v202, v136, v137
	v_cvt_pk_bf16_f32 v203, v138, v139
	v_cndmask_b32_dpp v216, v204, v200, vcc quad_perm:[1,0,3,2] row_mask:0xf bank_mask:0xf
	v_cndmask_b32_dpp v217, v205, v201, vcc quad_perm:[1,0,3,2] row_mask:0xf bank_mask:0xf
	v_cndmask_b32_dpp v218, v206, v202, vcc quad_perm:[1,0,3,2] row_mask:0xf bank_mask:0xf
	v_cndmask_b32_dpp v219, v207, v203, vcc quad_perm:[1,0,3,2] row_mask:0xf bank_mask:0xf
	s_not_b64 vcc, vcc
	v_cndmask_b32_dpp v220, v200, v204, vcc quad_perm:[1,0,3,2] row_mask:0xf bank_mask:0xf
	v_cndmask_b32_dpp v221, v201, v205, vcc quad_perm:[1,0,3,2] row_mask:0xf bank_mask:0xf
	v_cndmask_b32_dpp v222, v202, v206, vcc quad_perm:[1,0,3,2] row_mask:0xf bank_mask:0xf
	v_cndmask_b32_dpp v223, v203, v207, vcc quad_perm:[1,0,3,2] row_mask:0xf bank_mask:0xf
	s_not_b64 vcc, vcc
	global_store_dwordx4 v[130:131], v[216:219], off
	global_store_dwordx4 v[130:131], v[220:223], off offset:1024
	v_lshl_add_u64 v[130:131], v[130:131], 0, s[4:5]
	v_mul_f32_e32 v224, 0xbfb8aa3b, v22
	v_mul_f32_e32 v225, 0xbfb8aa3b, v23
	v_mul_f32_e32 v226, 0xbfb8aa3b, v24
	v_mul_f32_e32 v227, 0xbfb8aa3b, v25
	v_mul_f32_e32 v228, 0xbfb8aa3b, v18
	v_mul_f32_e32 v229, 0xbfb8aa3b, v19
	v_mul_f32_e32 v230, 0xbfb8aa3b, v20
	v_mul_f32_e32 v231, 0xbfb8aa3b, v21
	v_exp_f32_e32 v224, v224
	v_exp_f32_e32 v225, v225
	v_exp_f32_e32 v226, v226
	v_exp_f32_e32 v227, v227
	v_exp_f32_e32 v228, v228
	v_exp_f32_e32 v229, v229
	v_exp_f32_e32 v230, v230
	v_exp_f32_e32 v231, v231
	v_add_f32_e32 v224, 1.0, v224
	v_add_f32_e32 v225, 1.0, v225
	v_add_f32_e32 v226, 1.0, v226
	v_add_f32_e32 v227, 1.0, v227
	v_add_f32_e32 v228, 1.0, v228
	v_add_f32_e32 v229, 1.0, v229
; __device__ __forceinline__ unsigned cvt_pk_bf16(float lo, float hi) { unsigned r; asm volatile("v_cvt_pk_bf16_f32 %0, %1, %2" : "=v"(r) : "v"(lo), "v"(hi)); return r; }
; __device__ __forceinline__ float silu_f(float x) { return x * __builtin_amdgcn_rcpf(1.f + __expf(-x)); }
;     __device__ __forceinline__ void operator()(const f32x4 (&acc)[2][2][4][2], const pg8::Unit& u, int wr, int wc, int fr, int fq) const {
;     ...
;                     bf16_t* rowp = base + (size_t)(row0 + ai * 128 + m * 16) * 512 + col0;
; #pragma unroll
;                     for (int bj = 0; bj < 2; ++bj) { f32x4 v0 = acc[ai][bj][m][0], v1 = acc[ai][bj][m][1];
;                         if (act) { v0 = (f32x4){silu_f(v0[0]), silu_f(v0[1]), silu_f(v0[2]), silu_f(v0[3])}; v1 = (f32x4){silu_f(v1[0]), silu_f(v1[1]), silu_f(v1[2]), silu_f(v1[3])}; }
;                         u32x4 w; w.x = cvt_pk_bf16(v0[0], v0[1]); w.y = cvt_pk_bf16(v0[2], v0[3]); w.z = cvt_pk_bf16(v1[0], v1[1]); w.w = cvt_pk_bf16(v1[2], v1[3]);
;                         *(u32x4*)(rowp + 32 * bj) = w; }
	v_add_f32_e32 v230, 1.0, v230
	v_add_f32_e32 v231, 1.0, v231
	v_rcp_f32_e32 v224, v224
	v_rcp_f32_e32 v225, v225
	v_rcp_f32_e32 v226, v226
	v_rcp_f32_e32 v227, v227
	v_rcp_f32_e32 v228, v228
	v_rcp_f32_e32 v229, v229
	v_rcp_f32_e32 v230, v230
	v_rcp_f32_e32 v231, v231
	v_pk_mul_f32 v[224:225], v[22:23], v[224:225]
	v_pk_mul_f32 v[226:227], v[24:25], v[226:227]
	v_pk_mul_f32 v[228:229], v[18:19], v[228:229]
	v_pk_mul_f32 v[230:231], v[20:21], v[230:231]
	v_cvt_pk_bf16_f32 v204, v224, v225
	v_cvt_pk_bf16_f32 v205, v226, v227
	v_cvt_pk_bf16_f32 v206, v228, v229
	v_cvt_pk_bf16_f32 v207, v230, v231
	v_mul_f32_e32 v132, 0xbfb8aa3b, v30
	v_mul_f32_e32 v133, 0xbfb8aa3b, v31
	v_mul_f32_e32 v134, 0xbfb8aa3b, v32
	v_mul_f32_e32 v135, 0xbfb8aa3b, v33
	v_mul_f32_e32 v136, 0xbfb8aa3b, v26
	v_mul_f32_e32 v137, 0xbfb8aa3b, v27
	v_mul_f32_e32 v138, 0xbfb8aa3b, v28
	v_mul_f32_e32 v139, 0xbfb8aa3b, v29
	v_exp_f32_e32 v132, v132
	v_exp_f32_e32 v133, v133
	v_exp_f32_e32 v134, v134
	v_exp_f32_e32 v135, v135
	v_exp_f32_e32 v136, v136
	v_exp_f32_e32 v137, v137
	v_exp_f32_e32 v138, v138
	v_exp_f32_e32 v139, v139
	v_add_f32_e32 v132, 1.0, v132
	v_add_f32_e32 v133, 1.0, v133
	v_add_f32_e32 v134, 1.0, v134
	v_add_f32_e32 v135, 1.0, v135
	v_add_f32_e32 v136, 1.0, v136
	v_add_f32_e32 v137, 1.0, v137
	v_add_f32_e32 v138, 1.0, v138
	v_add_f32_e32 v139, 1.0, v139
	v_rcp_f32_e32 v132, v132
	v_rcp_f32_e32 v133, v133
	v_rcp_f32_e32 v134, v134
	v_rcp_f32_e32 v135, v135
	v_rcp_f32_e32 v136, v136
	v_rcp_f32_e32 v137, v137
	v_rcp_f32_e32 v138, v138
	v_rcp_f32_e32 v139, v139
	v_pk_mul_f32 v[132:133], v[30:31], v[132:133]
	v_pk_mul_f32 v[134:135], v[32:33], v[134:135]
	v_pk_mul_f32 v[136:137], v[26:27], v[136:137]
	v_pk_mul_f32 v[138:139], v[28:29], v[138:139]
	v_cvt_pk_bf16_f32 v200, v132, v133
	v_cvt_pk_bf16_f32 v201, v134, v135
	v_cvt_pk_bf16_f32 v202, v136, v137
	v_cvt_pk_bf16_f32 v203, v138, v139
	v_cndmask_b32_dpp v208, v204, v200, vcc quad_perm:[1,0,3,2] row_mask:0xf bank_mask:0xf
	v_cndmask_b32_dpp v209, v205, v201, vcc quad_perm:[1,0,3,2] row_mask:0xf bank_mask:0xf
	v_cndmask_b32_dpp v210, v206, v202, vcc quad_perm:[1,0,3,2] row_mask:0xf bank_mask:0xf
	v_cndmask_b32_dpp v211, v207, v203, vcc quad_perm:[1,0,3,2] row_mask:0xf bank_mask:0xf
	s_not_b64 vcc, vcc
	v_cndmask_b32_dpp v212, v200, v204, vcc quad_perm:[1,0,3,2] row_mask:0xf bank_mask:0xf
	v_cndmask_b32_dpp v213, v201, v205, vcc quad_perm:[1,0,3,2] row_mask:0xf bank_mask:0xf
	v_cndmask_b32_dpp v214, v202, v206, vcc quad_perm:[1,0,3,2] row_mask:0xf bank_mask:0xf
	v_cndmask_b32_dpp v215, v203, v207, vcc quad_perm:[1,0,3,2] row_mask:0xf bank_mask:0xf
	s_not_b64 vcc, vcc
	global_store_dwordx4 v[130:131], v[208:211], off
	global_store_dwordx4 v[130:131], v[212:215], off offset:1024
	v_lshl_add_u64 v[130:131], v[130:131], 0, s[4:5]
	v_mul_f32_e32 v224, 0xbfb8aa3b, v6
	v_mul_f32_e32 v225, 0xbfb8aa3b, v7
	v_mul_f32_e32 v226, 0xbfb8aa3b, v8
	v_mul_f32_e32 v227, 0xbfb8aa3b, v9
	v_mul_f32_e32 v228, 0xbfb8aa3b, v2
	v_mul_f32_e32 v229, 0xbfb8aa3b, v3
	v_mul_f32_e32 v230, 0xbfb8aa3b, v4
	v_mul_f32_e32 v231, 0xbfb8aa3b, v5
	v_exp_f32_e32 v224, v224
	v_exp_f32_e32 v225, v225
	v_exp_f32_e32 v226, v226
	v_exp_f32_e32 v227, v227
	v_exp_f32_e32 v228, v228
	v_exp_f32_e32 v229, v229
	v_exp_f32_e32 v230, v230
	v_exp_f32_e32 v231, v231
	v_add_f32_e32 v224, 1.0, v224
	v_add_f32_e32 v225, 1.0, v225
	v_add_f32_e32 v226, 1.0, v226
	v_add_f32_e32 v227, 1.0, v227
	v_add_f32_e32 v228, 1.0, v228
	v_add_f32_e32 v229, 1.0, v229
	v_add_f32_e32 v230, 1.0, v230
	v_add_f32_e32 v231, 1.0, v231
	v_rcp_f32_e32 v224, v224
	v_rcp_f32_e32 v225, v225
	v_rcp_f32_e32 v226, v226
	v_rcp_f32_e32 v227, v227
	v_rcp_f32_e32 v228, v228
	v_rcp_f32_e32 v229, v229
	v_rcp_f32_e32 v230, v230
	v_rcp_f32_e32 v231, v231
	v_pk_mul_f32 v[224:225], v[6:7], v[224:225]
	v_pk_mul_f32 v[226:227], v[8:9], v[226:227]
	v_pk_mul_f32 v[228:229], v[2:3], v[228:229]
	v_pk_mul_f32 v[230:231], v[4:5], v[230:231]
	v_cvt_pk_bf16_f32 v204, v224, v225
	v_cvt_pk_bf16_f32 v205, v226, v227
	v_cvt_pk_bf16_f32 v206, v228, v229
	v_cvt_pk_bf16_f32 v207, v230, v231
	v_mul_f32_e32 v132, 0xbfb8aa3b, v14
	v_mul_f32_e32 v133, 0xbfb8aa3b, v15
	v_mul_f32_e32 v134, 0xbfb8aa3b, v16
	v_mul_f32_e32 v135, 0xbfb8aa3b, v17
	v_mul_f32_e32 v136, 0xbfb8aa3b, v10
	v_mul_f32_e32 v137, 0xbfb8aa3b, v11
	v_mul_f32_e32 v138, 0xbfb8aa3b, v12
	v_mul_f32_e32 v139, 0xbfb8aa3b, v13
	v_exp_f32_e32 v132, v132
	v_exp_f32_e32 v133, v133
	v_exp_f32_e32 v134, v134
	v_exp_f32_e32 v135, v135
	v_exp_f32_e32 v136, v136
	v_exp_f32_e32 v137, v137
	v_exp_f32_e32 v138, v138
	v_exp_f32_e32 v139, v139
	v_add_f32_e32 v132, 1.0, v132
	v_add_f32_e32 v133, 1.0, v133
	v_add_f32_e32 v134, 1.0, v134
	v_add_f32_e32 v135, 1.0, v135
	v_add_f32_e32 v136, 1.0, v136
	v_add_f32_e32 v137, 1.0, v137
	v_add_f32_e32 v138, 1.0, v138
	v_add_f32_e32 v139, 1.0, v139
	v_rcp_f32_e32 v132, v132
	v_rcp_f32_e32 v133, v133
	v_rcp_f32_e32 v134, v134
	v_rcp_f32_e32 v135, v135
	v_rcp_f32_e32 v136, v136
	v_rcp_f32_e32 v137, v137
	v_rcp_f32_e32 v138, v138
	v_rcp_f32_e32 v139, v139
	v_pk_mul_f32 v[132:133], v[14:15], v[132:133]
	v_pk_mul_f32 v[134:135], v[16:17], v[134:135]
	v_pk_mul_f32 v[136:137], v[10:11], v[136:137]
	v_pk_mul_f32 v[138:139], v[12:13], v[138:139]
	v_cvt_pk_bf16_f32 v200, v132, v133
	v_cvt_pk_bf16_f32 v201, v134, v135
	v_cvt_pk_bf16_f32 v202, v136, v137
	v_cvt_pk_bf16_f32 v203, v138, v139
	v_cndmask_b32_dpp v216, v204, v200, vcc quad_perm:[1,0,3,2] row_mask:0xf bank_mask:0xf
	v_cndmask_b32_dpp v217, v205, v201, vcc quad_perm:[1,0,3,2] row_mask:0xf bank_mask:0xf
	v_cndmask_b32_dpp v218, v206, v202, vcc quad_perm:[1,0,3,2] row_mask:0xf bank_mask:0xf
	v_cndmask_b32_dpp v219, v207, v203, vcc quad_perm:[1,0,3,2] row_mask:0xf bank_mask:0xf
	s_not_b64 vcc, vcc
	v_cndmask_b32_dpp v220, v200, v204, vcc quad_perm:[1,0,3,2] row_mask:0xf bank_mask:0xf
	v_cndmask_b32_dpp v221, v201, v205, vcc quad_perm:[1,0,3,2] row_mask:0xf bank_mask:0xf
	v_cndmask_b32_dpp v222, v202, v206, vcc quad_perm:[1,0,3,2] row_mask:0xf bank_mask:0xf
	v_cndmask_b32_dpp v223, v203, v207, vcc quad_perm:[1,0,3,2] row_mask:0xf bank_mask:0xf
	s_not_b64 vcc, vcc
	global_store_dwordx4 v[130:131], v[216:219], off
	global_store_dwordx4 v[130:131], v[220:223], off offset:1024
	s_branch .Lp1e_done

; __device__ __forceinline__ unsigned cvt_pk_bf16(float lo, float hi) { unsigned r; asm volatile("v_cvt_pk_bf16_f32 %0, %1, %2" : "=v"(r) : "v"(lo), "v"(hi)); return r; }
;     __device__ __forceinline__ void operator()(const f32x4 (&acc)[2][2][4][2], const pg8::Unit& u, int wr, int wc, int fr, int fq) const {
;     ...
;         } else if (sec == 4 || sec == 5) {
;             const float osc = sec == 5 ? 0.08838834764831845f : 1.f;
;             const int col0 = 256 * half + 128 * (wc >> 1) + 32 * (wc & 1) + 8 * fq, i0 = 32 * (wc & 1) + 8 * fq;
;             const int tb = row0 < NP ? (row0 & 4095) : row0 - NP;
;             f32x4 c[2], sn[2], c16[2], s16[2];
; #pragma unroll
;             for (int e = 0; e < 2; ++e) { c[e] = *(const f32x4*)(ropec + tb * 64 + i0 + 4 * e); sn[e] = *(const f32x4*)(ropes + tb * 64 + i0 + 4 * e);
;                 c16[e] = *(const f32x4*)(ropec + 16 * 64 + i0 + 4 * e); s16[e] = *(const f32x4*)(ropes + 16 * 64 + i0 + 4 * e); }
;             asm volatile("" ::: "memory");
; #pragma unroll
;             for (int k = 0; k < 12; ++k) {
;                 if (k < 4 || k >= 8) {
;                     const int ai = k >> 3, m = k & 3;
;                     const int row = row0 + ai * 128 + m * 16;
;                     const f32x4 c0 = c[0] * osc, c1 = c[1] * osc, s0 = sn[0] * osc, s1 = sn[1] * osc;
;                     const f32x4 a0 = acc[ai][0][m][0], a1 = acc[ai][0][m][1], b0 = acc[ai][1][m][0], b1 = acc[ai][1][m][1];
;                     const f32x4 o10 = a0 * c0 - b0 * s0, o11 = a1 * c1 - b1 * s1, o20 = a0 * s0 + b0 * c0, o21 = a1 * s1 + b1 * c1;
;                     bf16_t* rowp = base + (size_t)row * 512 + col0;
;                     u32x4 w; w.x = cvt_pk_bf16(o10[0], o10[1]); w.y = cvt_pk_bf16(o10[2], o10[3]); w.z = cvt_pk_bf16(o11[0], o11[1]); w.w = cvt_pk_bf16(o11[2], o11[3]);
;                     *(u32x4*)(rowp) = w;
;                     w.x = cvt_pk_bf16(o20[0], o20[1]); w.y = cvt_pk_bf16(o20[2], o20[3]); w.z = cvt_pk_bf16(o21[0], o21[1]); w.w = cvt_pk_bf16(o21[2], o21[3]);
;                     *(u32x4*)(rowp + 64) = w;
.LBB0_202:
	s_and_b64 vcc, exec, s[4:5]
	s_cbranch_vccz .LBB0_204
	v_and_b32_e32 v130, 0xfcf, v172
	v_add_u32_e32 v131, 0xffff0000, v172
	v_cmp_gt_i32_e32 vcc, s77, v172
	s_cmp_eq_u32 s41, 5
	v_lshl_or_b32 v154, s27, 9, v186
	v_cndmask_b32_e32 v130, v131, v130, vcc
	v_lshlrev_b32_e32 v130, 6, v130
	v_ashrrev_i32_e32 v131, 31, v130
	v_lshlrev_b64 v[130:131], 2, v[130:131]
	v_lshl_add_u64 v[132:133], v[156:157], 0, v[130:131]
	global_load_dwordx4 v[192:195], v[132:133], off
	global_load_dwordx4 v[196:199], v[132:133], off offset:16
	v_lshl_add_u64 v[130:131], v[158:159], 0, v[130:131]
	global_load_dwordx4 v[200:203], v[130:131], off
	global_load_dwordx4 v[204:207], v[130:131], off offset:16
	global_load_dwordx4 v[142:145], v[162:163], off
	global_load_dwordx4 v[134:137], v[162:163], off offset:16
	global_load_dwordx4 v[138:141], v[160:161], off
	s_nop 0
	global_load_dwordx4 v[130:133], v[160:161], off offset:16
	s_cselect_b64 vcc, -1, 0
	v_cndmask_b32_e32 v176, 1.0, v189, vcc
	v_ashrrev_i32_e32 v173, 31, v172
	v_lshl_add_u64 v[178:179], s[48:49], 0, v[154:155]
	v_lshlrev_b64 v[174:175], 10, v[172:173]
	v_lshl_add_u64 v[174:175], v[178:179], 0, v[174:175]
	v_or_b32_e32 v208, 16, v172
	v_ashrrev_i32_e32 v209, 31, v208
	s_waitcnt vmcnt(0)
	s_add_i32 m0, s47, 0xc000
	s_nop 0
	global_load_lds_dwordx4 v164, s[94:95]
	s_add_i32 m0, s47, 0xe000
	s_nop 0
	global_load_lds_dwordx4 v166, s[94:95]
	v_pk_mul_f32 v[220:221], v[176:177], v[200:201] op_sel_hi:[0,1]
	v_pk_mul_f32 v[218:219], v[176:177], v[202:203] op_sel_hi:[0,1]
	v_pk_mul_f32 v[212:213], v[176:177], v[192:193] op_sel_hi:[0,1]
	v_pk_mul_f32 v[228:229], v[200:201], v[142:143]
	v_pk_mul_f32 v[244:245], v[118:119], v[220:221]
	v_pk_mul_f32 v[210:211], v[176:177], v[194:195] op_sel_hi:[0,1]
	v_pk_mul_f32 v[222:223], v[176:177], v[206:207] op_sel_hi:[0,1]
	v_pk_mul_f32 v[224:225], v[176:177], v[204:205] op_sel_hi:[0,1]
	v_pk_mul_f32 v[226:227], v[202:203], v[144:145]
	v_pk_mul_f32 v[230:231], v[194:195], v[144:145]
	v_pk_mul_f32 v[232:233], v[192:193], v[142:143]
	v_pk_mul_f32 v[242:243], v[120:121], v[218:219]
	v_pk_fma_f32 v[228:229], v[192:193], v[138:139], v[228:229] neg_lo:[0,0,1] neg_hi:[0,0,1]
	v_pk_fma_f32 v[192:193], v[126:127], v[212:213], v[244:245] neg_lo:[0,0,1] neg_hi:[0,0,1]
	v_pk_mul_f32 v[214:215], v[176:177], v[198:199] op_sel_hi:[0,1]
	v_pk_mul_f32 v[216:217], v[176:177], v[196:197] op_sel_hi:[0,1]
	v_pk_mul_f32 v[234:235], v[206:207], v[136:137]
	v_pk_mul_f32 v[238:239], v[198:199], v[136:137]
	v_pk_mul_f32 v[240:241], v[196:197], v[134:135]
	v_pk_mul_f32 v[246:247], v[116:117], v[222:223]
	v_pk_mul_f32 v[248:249], v[114:115], v[224:225]
	v_pk_mul_f32 v[218:219], v[128:129], v[218:219]
	v_pk_mul_f32 v[220:221], v[126:127], v[220:221]
	v_pk_fma_f32 v[226:227], v[194:195], v[140:141], v[226:227] neg_lo:[0,0,1] neg_hi:[0,0,1]
	v_pk_fma_f32 v[202:203], v[202:203], v[140:141], v[230:231]
	v_pk_fma_f32 v[194:195], v[128:129], v[210:211], v[242:243] neg_lo:[0,0,1] neg_hi:[0,0,1]
	v_cvt_pk_bf16_f32 v192, v192, v193
	v_pk_mul_f32 v[236:237], v[204:205], v[134:135]
	v_cvt_pk_bf16_f32 v193, v194, v195
	v_pk_mul_f32 v[222:223], v[124:125], v[222:223]
	v_pk_mul_f32 v[224:225], v[122:123], v[224:225]
	v_pk_fma_f32 v[200:201], v[200:201], v[138:139], v[232:233]
	v_pk_fma_f32 v[198:199], v[198:199], v[132:133], v[234:235] neg_lo:[0,0,1] neg_hi:[0,0,1]
	v_pk_fma_f32 v[206:207], v[206:207], v[132:133], v[238:239]
	v_pk_fma_f32 v[204:205], v[204:205], v[130:131], v[240:241]
	v_pk_fma_f32 v[230:231], v[124:125], v[214:215], v[246:247] neg_lo:[0,0,1] neg_hi:[0,0,1]
	v_pk_fma_f32 v[232:233], v[122:123], v[216:217], v[248:249] neg_lo:[0,0,1] neg_hi:[0,0,1]
	v_pk_fma_f32 v[210:211], v[120:121], v[210:211], v[218:219]
	v_pk_fma_f32 v[212:213], v[118:119], v[212:213], v[220:221]
	v_pk_mul_f32 v[218:219], v[176:177], v[226:227] op_sel_hi:[0,1]
	v_pk_mul_f32 v[234:235], v[176:177], v[202:203] op_sel_hi:[0,1]
	v_cvt_pk_bf16_f32 v194, v232, v233
	v_cvt_pk_bf16_f32 v195, v230, v231
	global_store_dwordx4 v[174:175], v[192:195], off
	v_pk_fma_f32 v[196:197], v[196:197], v[130:131], v[236:237] neg_lo:[0,0,1] neg_hi:[0,0,1]
	v_pk_fma_f32 v[214:215], v[116:117], v[214:215], v[222:223]
	v_cvt_pk_bf16_f32 v192, v212, v213
	v_cvt_pk_bf16_f32 v193, v210, v211
	v_pk_fma_f32 v[216:217], v[114:115], v[216:217], v[224:225]
	v_pk_mul_f32 v[222:223], v[176:177], v[198:199] op_sel_hi:[0,1]
	v_pk_mul_f32 v[238:239], v[176:177], v[206:207] op_sel_hi:[0,1]
	v_pk_mul_f32 v[240:241], v[176:177], v[204:205] op_sel_hi:[0,1]
	v_pk_mul_f32 v[230:231], v[104:105], v[234:235]
	v_cvt_pk_bf16_f32 v194, v216, v217
	v_cvt_pk_bf16_f32 v195, v214, v215
	global_store_dwordx4 v[174:175], v[192:195], off offset:128
	v_pk_mul_f32 v[224:225], v[176:177], v[196:197] op_sel_hi:[0,1]
	v_pk_mul_f32 v[236:237], v[176:177], v[200:201] op_sel_hi:[0,1]
	v_pk_mul_f32 v[192:193], v[104:105], v[218:219]
	v_pk_mul_f32 v[242:243], v[100:101], v[238:239]
	v_pk_mul_f32 v[244:245], v[98:99], v[240:241]
	v_pk_fma_f32 v[210:211], v[112:113], v[218:219], v[230:231] neg_lo:[0,0,1] neg_hi:[0,0,1]
	v_pk_fma_f32 v[218:219], v[112:113], v[234:235], v[192:193]
	v_pk_mul_f32 v[192:193], v[100:101], v[222:223]
	v_pk_mul_f32 v[220:221], v[176:177], v[228:229] op_sel_hi:[0,1]
	v_pk_mul_f32 v[232:233], v[102:103], v[236:237]
	v_pk_fma_f32 v[214:215], v[108:109], v[222:223], v[242:243] neg_lo:[0,0,1] neg_hi:[0,0,1]
	v_pk_fma_f32 v[194:195], v[106:107], v[224:225], v[244:245] neg_lo:[0,0,1] neg_hi:[0,0,1]
	v_pk_fma_f32 v[222:223], v[108:109], v[238:239], v[192:193]
	v_lshlrev_b64 v[192:193], 10, v[208:209]
	v_pk_fma_f32 v[212:213], v[110:111], v[220:221], v[232:233] neg_lo:[0,0,1] neg_hi:[0,0,1]
; __device__ __forceinline__ unsigned cvt_pk_bf16(float lo, float hi) { unsigned r; asm volatile("v_cvt_pk_bf16_f32 %0, %1, %2" : "=v"(r) : "v"(lo), "v"(hi)); return r; }
;     __device__ __forceinline__ void operator()(const f32x4 (&acc)[2][2][4][2], const pg8::Unit& u, int wr, int wc, int fr, int fq) const {
;     ...
; #pragma unroll
;             for (int k = 0; k < 12; ++k) {
;                 if (k < 4 || k >= 8) {
;                     const int ai = k >> 3, m = k & 3;
;                     const int row = row0 + ai * 128 + m * 16;
;                     const f32x4 c0 = c[0] * osc, c1 = c[1] * osc, s0 = sn[0] * osc, s1 = sn[1] * osc;
;                     const f32x4 a0 = acc[ai][0][m][0], a1 = acc[ai][0][m][1], b0 = acc[ai][1][m][0], b1 = acc[ai][1][m][1];
;                     const f32x4 o10 = a0 * c0 - b0 * s0, o11 = a1 * c1 - b1 * s1, o20 = a0 * s0 + b0 * c0, o21 = a1 * s1 + b1 * c1;
;                     bf16_t* rowp = base + (size_t)row * 512 + col0;
;                     u32x4 w; w.x = cvt_pk_bf16(o10[0], o10[1]); w.y = cvt_pk_bf16(o10[2], o10[3]); w.z = cvt_pk_bf16(o11[0], o11[1]); w.w = cvt_pk_bf16(o11[2], o11[3]);
;                     *(u32x4*)(rowp) = w;
;                     w.x = cvt_pk_bf16(o20[0], o20[1]); w.y = cvt_pk_bf16(o20[2], o20[3]); w.z = cvt_pk_bf16(o21[0], o21[1]); w.w = cvt_pk_bf16(o21[2], o21[3]);
;                     *(u32x4*)(rowp + 64) = w;
;                 }
;                 if (k < 11) {
; #pragma unroll
;                     for (int e = 0; e < 2; ++e) { const f32x4 cn = c[e] * c16[e] - sn[e] * s16[e]; sn[e] = sn[e] * c16[e] + c[e] * s16[e]; c[e] = cn; } }
	v_pk_mul_f32 v[216:217], v[102:103], v[220:221]
	v_pk_mul_f32 v[220:221], v[98:99], v[224:225]
	v_lshl_add_u64 v[208:209], v[178:179], 0, v[192:193]
	v_cvt_pk_bf16_f32 v192, v212, v213
	v_cvt_pk_bf16_f32 v193, v210, v211
	v_cvt_pk_bf16_f32 v194, v194, v195
	v_cvt_pk_bf16_f32 v195, v214, v215
	v_pk_fma_f32 v[216:217], v[110:111], v[236:237], v[216:217]
	v_pk_fma_f32 v[220:221], v[106:107], v[240:241], v[220:221]
	global_store_dwordx4 v[208:209], v[192:195], off
	s_nop 1
	v_cvt_pk_bf16_f32 v192, v216, v217
	v_cvt_pk_bf16_f32 v193, v218, v219
	v_cvt_pk_bf16_f32 v194, v220, v221
	v_cvt_pk_bf16_f32 v195, v222, v223
	global_store_dwordx4 v[208:209], v[192:195], off offset:128
	s_nop 1
	v_pk_mul_f32 v[192:193], v[144:145], v[202:203]
	v_pk_mul_f32 v[194:195], v[142:143], v[200:201]
	v_pk_fma_f32 v[208:209], v[140:141], v[226:227], v[192:193] neg_lo:[0,0,1] neg_hi:[0,0,1]
	v_pk_fma_f32 v[210:211], v[138:139], v[228:229], v[194:195] neg_lo:[0,0,1] neg_hi:[0,0,1]
	v_pk_mul_f32 v[192:193], v[144:145], v[226:227]
	v_pk_mul_f32 v[194:195], v[142:143], v[228:229]
	v_pk_fma_f32 v[202:203], v[140:141], v[202:203], v[192:193]
	v_pk_fma_f32 v[200:201], v[138:139], v[200:201], v[194:195]
	v_pk_mul_f32 v[192:193], v[136:137], v[206:207]
	v_pk_mul_f32 v[194:195], v[134:135], v[204:205]
	v_pk_fma_f32 v[212:213], v[132:133], v[198:199], v[192:193] neg_lo:[0,0,1] neg_hi:[0,0,1]
	v_pk_fma_f32 v[214:215], v[130:131], v[196:197], v[194:195] neg_lo:[0,0,1] neg_hi:[0,0,1]
	v_pk_mul_f32 v[192:193], v[136:137], v[198:199]
	v_pk_mul_f32 v[194:195], v[134:135], v[196:197]
	v_pk_mul_f32 v[218:219], v[176:177], v[202:203] op_sel_hi:[0,1]
	v_pk_fma_f32 v[196:197], v[132:133], v[206:207], v[192:193]
	v_pk_fma_f32 v[198:199], v[130:131], v[204:205], v[194:195]
	v_or_b32_e32 v192, 32, v172
	v_pk_mul_f32 v[194:195], v[176:177], v[208:209] op_sel_hi:[0,1]
	v_pk_mul_f32 v[220:221], v[176:177], v[200:201] op_sel_hi:[0,1]
	v_pk_mul_f32 v[226:227], v[88:89], v[218:219]
	v_pk_mul_f32 v[204:205], v[176:177], v[210:211] op_sel_hi:[0,1]
	v_pk_mul_f32 v[206:207], v[176:177], v[212:213] op_sel_hi:[0,1]
	v_pk_mul_f32 v[222:223], v[176:177], v[196:197] op_sel_hi:[0,1]
	v_pk_mul_f32 v[224:225], v[176:177], v[198:199] op_sel_hi:[0,1]
	v_pk_mul_f32 v[228:229], v[86:87], v[220:221]
	v_pk_fma_f32 v[226:227], v[96:97], v[194:195], v[226:227] neg_lo:[0,0,1] neg_hi:[0,0,1]
	v_pk_mul_f32 v[194:195], v[88:89], v[194:195]
	v_ashrrev_i32_e32 v193, 31, v192
	v_pk_mul_f32 v[216:217], v[176:177], v[214:215] op_sel_hi:[0,1]
	v_pk_fma_f32 v[228:229], v[94:95], v[204:205], v[228:229] neg_lo:[0,0,1] neg_hi:[0,0,1]
	v_pk_mul_f32 v[230:231], v[84:85], v[222:223]
	v_pk_mul_f32 v[232:233], v[82:83], v[224:225]
	v_pk_mul_f32 v[204:205], v[86:87], v[204:205]
	v_pk_fma_f32 v[218:219], v[96:97], v[218:219], v[194:195]
	v_pk_mul_f32 v[194:195], v[84:85], v[206:207]
	v_lshlrev_b64 v[192:193], 10, v[192:193]
	v_pk_fma_f32 v[230:231], v[92:93], v[206:207], v[230:231] neg_lo:[0,0,1] neg_hi:[0,0,1]
	v_pk_fma_f32 v[232:233], v[90:91], v[216:217], v[232:233] neg_lo:[0,0,1] neg_hi:[0,0,1]
	v_pk_fma_f32 v[204:205], v[94:95], v[220:221], v[204:205]
	v_pk_mul_f32 v[206:207], v[82:83], v[216:217]
	v_pk_fma_f32 v[216:217], v[92:93], v[222:223], v[194:195]
	v_lshl_add_u64 v[220:221], v[178:179], 0, v[192:193]
	v_cvt_pk_bf16_f32 v192, v228, v229
	v_cvt_pk_bf16_f32 v193, v226, v227
	v_cvt_pk_bf16_f32 v194, v232, v233
	v_cvt_pk_bf16_f32 v195, v230, v231
	v_pk_fma_f32 v[206:207], v[90:91], v[224:225], v[206:207]
	global_store_dwordx4 v[220:221], v[192:195], off
	s_nop 1
	v_cvt_pk_bf16_f32 v192, v204, v205
	v_cvt_pk_bf16_f32 v193, v218, v219
	v_cvt_pk_bf16_f32 v194, v206, v207
	v_cvt_pk_bf16_f32 v195, v216, v217
	global_store_dwordx4 v[220:221], v[192:195], off offset:128
	s_nop 1
	v_pk_mul_f32 v[192:193], v[144:145], v[202:203]
	v_pk_mul_f32 v[194:195], v[142:143], v[200:201]
	v_pk_fma_f32 v[204:205], v[140:141], v[208:209], v[192:193] neg_lo:[0,0,1] neg_hi:[0,0,1]
	v_pk_fma_f32 v[206:207], v[138:139], v[210:211], v[194:195] neg_lo:[0,0,1] neg_hi:[0,0,1]
	v_pk_mul_f32 v[192:193], v[144:145], v[208:209]
	v_pk_mul_f32 v[194:195], v[142:143], v[210:211]
	v_pk_fma_f32 v[202:203], v[140:141], v[202:203], v[192:193]
	v_pk_fma_f32 v[200:201], v[138:139], v[200:201], v[194:195]
	v_pk_mul_f32 v[192:193], v[136:137], v[196:197]
	v_pk_mul_f32 v[194:195], v[134:135], v[198:199]
	v_pk_fma_f32 v[208:209], v[132:133], v[212:213], v[192:193] neg_lo:[0,0,1] neg_hi:[0,0,1]
	v_pk_fma_f32 v[210:211], v[130:131], v[214:215], v[194:195] neg_lo:[0,0,1] neg_hi:[0,0,1]
	v_pk_mul_f32 v[192:193], v[136:137], v[212:213]
	v_pk_mul_f32 v[194:195], v[134:135], v[214:215]
	v_pk_mul_f32 v[218:219], v[176:177], v[202:203] op_sel_hi:[0,1]
	v_pk_fma_f32 v[196:197], v[132:133], v[196:197], v[192:193]
	v_pk_fma_f32 v[198:199], v[130:131], v[198:199], v[194:195]
	v_or_b32_e32 v192, 48, v172
	v_pk_mul_f32 v[194:195], v[176:177], v[204:205] op_sel_hi:[0,1]
	v_pk_mul_f32 v[226:227], v[72:73], v[218:219]
	v_pk_mul_f32 v[214:215], v[176:177], v[208:209] op_sel_hi:[0,1]
	v_pk_mul_f32 v[220:221], v[176:177], v[200:201] op_sel_hi:[0,1]
	v_pk_mul_f32 v[222:223], v[176:177], v[196:197] op_sel_hi:[0,1]
	v_pk_mul_f32 v[224:225], v[176:177], v[198:199] op_sel_hi:[0,1]
	v_pk_fma_f32 v[226:227], v[80:81], v[194:195], v[226:227] neg_lo:[0,0,1] neg_hi:[0,0,1]
	v_pk_mul_f32 v[194:195], v[72:73], v[194:195]
	v_ashrrev_i32_e32 v193, 31, v192
	v_pk_mul_f32 v[212:213], v[176:177], v[206:207] op_sel_hi:[0,1]
	v_pk_mul_f32 v[216:217], v[176:177], v[210:211] op_sel_hi:[0,1]
	v_pk_mul_f32 v[228:229], v[70:71], v[220:221]
	v_pk_mul_f32 v[230:231], v[68:69], v[222:223]
	v_pk_mul_f32 v[232:233], v[66:67], v[224:225]
; __device__ __forceinline__ unsigned cvt_pk_bf16(float lo, float hi) { unsigned r; asm volatile("v_cvt_pk_bf16_f32 %0, %1, %2" : "=v"(r) : "v"(lo), "v"(hi)); return r; }
;     __device__ __forceinline__ void operator()(const f32x4 (&acc)[2][2][4][2], const pg8::Unit& u, int wr, int wc, int fr, int fq) const {
;     ...
;             for (int k = 0; k < 12; ++k) {
;                 if (k < 4 || k >= 8) {
;                     const int ai = k >> 3, m = k & 3;
;                     const int row = row0 + ai * 128 + m * 16;
;                     const f32x4 c0 = c[0] * osc, c1 = c[1] * osc, s0 = sn[0] * osc, s1 = sn[1] * osc;
;                     const f32x4 a0 = acc[ai][0][m][0], a1 = acc[ai][0][m][1], b0 = acc[ai][1][m][0], b1 = acc[ai][1][m][1];
;                     const f32x4 o10 = a0 * c0 - b0 * s0, o11 = a1 * c1 - b1 * s1, o20 = a0 * s0 + b0 * c0, o21 = a1 * s1 + b1 * c1;
;                     bf16_t* rowp = base + (size_t)row * 512 + col0;
;                     u32x4 w; w.x = cvt_pk_bf16(o10[0], o10[1]); w.y = cvt_pk_bf16(o10[2], o10[3]); w.z = cvt_pk_bf16(o11[0], o11[1]); w.w = cvt_pk_bf16(o11[2], o11[3]);
;                     *(u32x4*)(rowp) = w;
;                     w.x = cvt_pk_bf16(o20[0], o20[1]); w.y = cvt_pk_bf16(o20[2], o20[3]); w.z = cvt_pk_bf16(o21[0], o21[1]); w.w = cvt_pk_bf16(o21[2], o21[3]);
;                     *(u32x4*)(rowp + 64) = w;
;                 }
;                 if (k < 11) {
; #pragma unroll
;                     for (int e = 0; e < 2; ++e) { const f32x4 cn = c[e] * c16[e] - sn[e] * s16[e]; sn[e] = sn[e] * c16[e] + c[e] * s16[e]; c[e] = cn; } }
;             }
	v_pk_fma_f32 v[218:219], v[80:81], v[218:219], v[194:195]
	v_pk_mul_f32 v[194:195], v[68:69], v[214:215]
	v_lshlrev_b64 v[192:193], 10, v[192:193]
	v_pk_fma_f32 v[228:229], v[78:79], v[212:213], v[228:229] neg_lo:[0,0,1] neg_hi:[0,0,1]
	v_pk_fma_f32 v[230:231], v[76:77], v[214:215], v[230:231] neg_lo:[0,0,1] neg_hi:[0,0,1]
	v_pk_fma_f32 v[232:233], v[74:75], v[216:217], v[232:233] neg_lo:[0,0,1] neg_hi:[0,0,1]
	v_pk_mul_f32 v[212:213], v[70:71], v[212:213]
	v_pk_mul_f32 v[214:215], v[66:67], v[216:217]
	v_pk_fma_f32 v[216:217], v[76:77], v[222:223], v[194:195]
	v_lshl_add_u64 v[178:179], v[178:179], 0, v[192:193]
	v_cvt_pk_bf16_f32 v192, v228, v229
	v_cvt_pk_bf16_f32 v193, v226, v227
	v_cvt_pk_bf16_f32 v194, v232, v233
	v_cvt_pk_bf16_f32 v195, v230, v231
	v_pk_fma_f32 v[212:213], v[78:79], v[220:221], v[212:213]
	v_pk_fma_f32 v[214:215], v[74:75], v[224:225], v[214:215]
	global_store_dwordx4 v[178:179], v[192:195], off
	s_nop 1
	v_cvt_pk_bf16_f32 v192, v212, v213
	v_cvt_pk_bf16_f32 v193, v218, v219
	v_cvt_pk_bf16_f32 v194, v214, v215
	v_cvt_pk_bf16_f32 v195, v216, v217
	global_store_dwordx4 v[178:179], v[192:195], off offset:128
	v_pk_mul_f32 v[178:179], v[144:145], v[202:203]
	s_nop 0
	v_pk_mul_f32 v[194:195], v[144:145], v[204:205]
	v_pk_mul_f32 v[192:193], v[142:143], v[200:201]
	v_pk_fma_f32 v[178:179], v[140:141], v[204:205], v[178:179] neg_lo:[0,0,1] neg_hi:[0,0,1]
	v_pk_mul_f32 v[204:205], v[142:143], v[206:207]
	v_pk_fma_f32 v[194:195], v[140:141], v[202:203], v[194:195]
	v_pk_mul_f32 v[202:203], v[136:137], v[196:197]
	v_pk_fma_f32 v[192:193], v[138:139], v[206:207], v[192:193] neg_lo:[0,0,1] neg_hi:[0,0,1]
	v_pk_fma_f32 v[200:201], v[138:139], v[200:201], v[204:205]
	v_pk_fma_f32 v[202:203], v[132:133], v[208:209], v[202:203] neg_lo:[0,0,1] neg_hi:[0,0,1]
	v_pk_mul_f32 v[206:207], v[136:137], v[208:209]
	v_pk_mul_f32 v[208:209], v[134:135], v[210:211]
	v_pk_mul_f32 v[204:205], v[134:135], v[198:199]
	v_pk_fma_f32 v[196:197], v[132:133], v[196:197], v[206:207]
	v_pk_fma_f32 v[198:199], v[130:131], v[198:199], v[208:209]
	v_pk_mul_f32 v[206:207], v[144:145], v[194:195]
	v_pk_mul_f32 v[208:209], v[142:143], v[200:201]
	v_pk_fma_f32 v[206:207], v[140:141], v[178:179], v[206:207] neg_lo:[0,0,1] neg_hi:[0,0,1]
	v_pk_fma_f32 v[208:209], v[138:139], v[192:193], v[208:209] neg_lo:[0,0,1] neg_hi:[0,0,1]
	v_pk_mul_f32 v[178:179], v[144:145], v[178:179]
	v_pk_mul_f32 v[192:193], v[142:143], v[192:193]
	v_pk_fma_f32 v[204:205], v[130:131], v[210:211], v[204:205] neg_lo:[0,0,1] neg_hi:[0,0,1]
	v_pk_fma_f32 v[178:179], v[140:141], v[194:195], v[178:179]
	v_pk_fma_f32 v[192:193], v[138:139], v[200:201], v[192:193]
	v_pk_mul_f32 v[194:195], v[136:137], v[196:197]
	v_pk_mul_f32 v[200:201], v[134:135], v[198:199]
	v_pk_fma_f32 v[194:195], v[132:133], v[202:203], v[194:195] neg_lo:[0,0,1] neg_hi:[0,0,1]
	v_pk_fma_f32 v[200:201], v[130:131], v[204:205], v[200:201] neg_lo:[0,0,1] neg_hi:[0,0,1]
	v_pk_mul_f32 v[202:203], v[136:137], v[202:203]
	v_pk_mul_f32 v[204:205], v[134:135], v[204:205]
	v_pk_fma_f32 v[196:197], v[132:133], v[196:197], v[202:203]
	v_pk_fma_f32 v[198:199], v[130:131], v[198:199], v[204:205]
	v_pk_mul_f32 v[202:203], v[144:145], v[178:179]
	v_pk_mul_f32 v[204:205], v[142:143], v[192:193]
	v_pk_fma_f32 v[202:203], v[140:141], v[206:207], v[202:203] neg_lo:[0,0,1] neg_hi:[0,0,1]
	v_pk_fma_f32 v[204:205], v[138:139], v[208:209], v[204:205] neg_lo:[0,0,1] neg_hi:[0,0,1]
	v_pk_mul_f32 v[206:207], v[144:145], v[206:207]
	v_pk_mul_f32 v[208:209], v[142:143], v[208:209]
	v_pk_fma_f32 v[178:179], v[140:141], v[178:179], v[206:207]
	v_pk_fma_f32 v[192:193], v[138:139], v[192:193], v[208:209]
	v_pk_mul_f32 v[206:207], v[136:137], v[196:197]
	v_pk_mul_f32 v[208:209], v[134:135], v[198:199]
	v_pk_fma_f32 v[206:207], v[132:133], v[194:195], v[206:207] neg_lo:[0,0,1] neg_hi:[0,0,1]
	v_pk_fma_f32 v[208:209], v[130:131], v[200:201], v[208:209] neg_lo:[0,0,1] neg_hi:[0,0,1]
	v_pk_mul_f32 v[194:195], v[136:137], v[194:195]
	v_pk_mul_f32 v[200:201], v[134:135], v[200:201]
	v_pk_fma_f32 v[194:195], v[132:133], v[196:197], v[194:195]
	v_pk_fma_f32 v[196:197], v[130:131], v[198:199], v[200:201]
	v_pk_mul_f32 v[198:199], v[144:145], v[178:179]
	v_pk_mul_f32 v[200:201], v[142:143], v[192:193]
	v_pk_fma_f32 v[198:199], v[140:141], v[202:203], v[198:199] neg_lo:[0,0,1] neg_hi:[0,0,1]
	v_pk_fma_f32 v[200:201], v[138:139], v[204:205], v[200:201] neg_lo:[0,0,1] neg_hi:[0,0,1]
	v_pk_mul_f32 v[202:203], v[144:145], v[202:203]
	v_pk_mul_f32 v[204:205], v[142:143], v[204:205]
	v_pk_fma_f32 v[178:179], v[140:141], v[178:179], v[202:203]
	v_pk_fma_f32 v[192:193], v[138:139], v[192:193], v[204:205]
	v_pk_mul_f32 v[202:203], v[136:137], v[194:195]
	v_pk_mul_f32 v[204:205], v[134:135], v[196:197]
	v_pk_fma_f32 v[202:203], v[132:133], v[206:207], v[202:203] neg_lo:[0,0,1] neg_hi:[0,0,1]
	v_pk_fma_f32 v[204:205], v[130:131], v[208:209], v[204:205] neg_lo:[0,0,1] neg_hi:[0,0,1]
	v_pk_mul_f32 v[206:207], v[136:137], v[206:207]
	v_pk_mul_f32 v[208:209], v[134:135], v[208:209]
	v_pk_fma_f32 v[194:195], v[132:133], v[194:195], v[206:207]
	v_pk_fma_f32 v[196:197], v[130:131], v[196:197], v[208:209]
	v_pk_mul_f32 v[206:207], v[144:145], v[178:179]
	v_pk_mul_f32 v[208:209], v[142:143], v[192:193]
	v_pk_fma_f32 v[206:207], v[140:141], v[198:199], v[206:207] neg_lo:[0,0,1] neg_hi:[0,0,1]
	v_pk_fma_f32 v[208:209], v[138:139], v[200:201], v[208:209] neg_lo:[0,0,1] neg_hi:[0,0,1]
	v_pk_mul_f32 v[198:199], v[144:145], v[198:199]
	v_pk_mul_f32 v[200:201], v[142:143], v[200:201]
	v_pk_fma_f32 v[178:179], v[140:141], v[178:179], v[198:199]
	v_pk_fma_f32 v[198:199], v[138:139], v[192:193], v[200:201]
; __device__ __forceinline__ unsigned cvt_pk_bf16(float lo, float hi) { unsigned r; asm volatile("v_cvt_pk_bf16_f32 %0, %1, %2" : "=v"(r) : "v"(lo), "v"(hi)); return r; }
;     __device__ __forceinline__ void operator()(const f32x4 (&acc)[2][2][4][2], const pg8::Unit& u, int wr, int wc, int fr, int fq) const {
;     ...
;             for (int k = 0; k < 12; ++k) {
;                 if (k < 4 || k >= 8) {
;                     const int ai = k >> 3, m = k & 3;
;                     const int row = row0 + ai * 128 + m * 16;
;                     const f32x4 c0 = c[0] * osc, c1 = c[1] * osc, s0 = sn[0] * osc, s1 = sn[1] * osc;
;                     const f32x4 a0 = acc[ai][0][m][0], a1 = acc[ai][0][m][1], b0 = acc[ai][1][m][0], b1 = acc[ai][1][m][1];
;                     const f32x4 o10 = a0 * c0 - b0 * s0, o11 = a1 * c1 - b1 * s1, o20 = a0 * s0 + b0 * c0, o21 = a1 * s1 + b1 * c1;
;                     bf16_t* rowp = base + (size_t)row * 512 + col0;
;                     u32x4 w; w.x = cvt_pk_bf16(o10[0], o10[1]); w.y = cvt_pk_bf16(o10[2], o10[3]); w.z = cvt_pk_bf16(o11[0], o11[1]); w.w = cvt_pk_bf16(o11[2], o11[3]);
;                     *(u32x4*)(rowp) = w;
;                     w.x = cvt_pk_bf16(o20[0], o20[1]); w.y = cvt_pk_bf16(o20[2], o20[3]); w.z = cvt_pk_bf16(o21[0], o21[1]); w.w = cvt_pk_bf16(o21[2], o21[3]);
;                     *(u32x4*)(rowp + 64) = w;
;                 }
;                 if (k < 11) {
; #pragma unroll
;                     for (int e = 0; e < 2; ++e) { const f32x4 cn = c[e] * c16[e] - sn[e] * s16[e]; sn[e] = sn[e] * c16[e] + c[e] * s16[e]; c[e] = cn; } }
;             }
	v_pk_mul_f32 v[192:193], v[136:137], v[194:195]
	v_pk_mul_f32 v[200:201], v[134:135], v[196:197]
	v_pk_fma_f32 v[210:211], v[132:133], v[202:203], v[192:193] neg_lo:[0,0,1] neg_hi:[0,0,1]
	v_pk_mul_f32 v[192:193], v[136:137], v[202:203]
	v_pk_mul_f32 v[202:203], v[134:135], v[204:205]
	v_pk_mul_f32 v[216:217], v[176:177], v[198:199] op_sel_hi:[0,1]
	v_pk_fma_f32 v[200:201], v[130:131], v[204:205], v[200:201] neg_lo:[0,0,1] neg_hi:[0,0,1]
	v_pk_fma_f32 v[204:205], v[132:133], v[194:195], v[192:193]
	v_pk_fma_f32 v[196:197], v[130:131], v[196:197], v[202:203]
	v_pk_mul_f32 v[194:195], v[176:177], v[208:209] op_sel_hi:[0,1]
	v_pk_mul_f32 v[214:215], v[176:177], v[178:179] op_sel_hi:[0,1]
	v_pk_mul_f32 v[224:225], v[54:55], v[216:217]
	v_pk_mul_f32 v[192:193], v[176:177], v[206:207] op_sel_hi:[0,1]
	v_pk_mul_f32 v[212:213], v[176:177], v[200:201] op_sel_hi:[0,1]
	v_pk_mul_f32 v[220:221], v[176:177], v[196:197] op_sel_hi:[0,1]
	v_pk_mul_f32 v[222:223], v[56:57], v[214:215]
	v_pk_fma_f32 v[224:225], v[62:63], v[194:195], v[224:225] neg_lo:[0,0,1] neg_hi:[0,0,1]
	v_pk_mul_f32 v[194:195], v[54:55], v[194:195]
	v_pk_mul_f32 v[202:203], v[176:177], v[210:211] op_sel_hi:[0,1]
	v_pk_mul_f32 v[218:219], v[176:177], v[204:205] op_sel_hi:[0,1]
	v_pk_fma_f32 v[222:223], v[64:65], v[192:193], v[222:223] neg_lo:[0,0,1] neg_hi:[0,0,1]
	v_pk_mul_f32 v[228:229], v[50:51], v[220:221]
	v_pk_mul_f32 v[192:193], v[56:57], v[192:193]
	v_pk_fma_f32 v[216:217], v[62:63], v[216:217], v[194:195]
	v_pk_mul_f32 v[194:195], v[50:51], v[212:213]
	v_pk_mul_f32 v[226:227], v[52:53], v[218:219]
	v_pk_fma_f32 v[228:229], v[58:59], v[212:213], v[228:229] neg_lo:[0,0,1] neg_hi:[0,0,1]
	v_pk_fma_f32 v[214:215], v[64:65], v[214:215], v[192:193]
	v_pk_mul_f32 v[192:193], v[52:53], v[202:203]
	v_pk_fma_f32 v[212:213], v[58:59], v[220:221], v[194:195]
	v_add_co_u32_e32 v220, vcc, s87, v174
	v_pk_fma_f32 v[226:227], v[60:61], v[202:203], v[226:227] neg_lo:[0,0,1] neg_hi:[0,0,1]
	v_pk_fma_f32 v[202:203], v[60:61], v[218:219], v[192:193]
	v_cvt_pk_bf16_f32 v192, v224, v225
	v_cvt_pk_bf16_f32 v193, v222, v223
	v_cvt_pk_bf16_f32 v194, v228, v229
	v_cvt_pk_bf16_f32 v195, v226, v227
	v_addc_co_u32_e32 v221, vcc, 0, v175, vcc
	v_lshl_add_u64 v[218:219], v[174:175], 0, s[16:17]
	global_store_dwordx4 v[220:221], v[192:195], off
	s_nop 1
	v_cvt_pk_bf16_f32 v192, v216, v217
	v_cvt_pk_bf16_f32 v193, v214, v215
	v_cvt_pk_bf16_f32 v194, v212, v213
	v_cvt_pk_bf16_f32 v195, v202, v203
	global_store_dwordx4 v[218:219], v[192:195], off offset:128
	s_nop 1
	v_pk_mul_f32 v[194:195], v[142:143], v[198:199]
	v_pk_mul_f32 v[192:193], v[144:145], v[178:179]
	v_pk_fma_f32 v[212:213], v[138:139], v[208:209], v[194:195] neg_lo:[0,0,1] neg_hi:[0,0,1]
	v_pk_mul_f32 v[194:195], v[142:143], v[208:209]
	v_pk_fma_f32 v[202:203], v[140:141], v[206:207], v[192:193] neg_lo:[0,0,1] neg_hi:[0,0,1]
	v_pk_mul_f32 v[192:193], v[144:145], v[206:207]
	v_pk_fma_f32 v[198:199], v[138:139], v[198:199], v[194:195]
	v_pk_mul_f32 v[194:195], v[134:135], v[196:197]
	v_pk_fma_f32 v[178:179], v[140:141], v[178:179], v[192:193]
	v_pk_mul_f32 v[192:193], v[136:137], v[204:205]
	v_pk_fma_f32 v[208:209], v[130:131], v[200:201], v[194:195] neg_lo:[0,0,1] neg_hi:[0,0,1]
	v_pk_mul_f32 v[194:195], v[134:135], v[200:201]
	v_pk_mul_f32 v[216:217], v[176:177], v[198:199] op_sel_hi:[0,1]
	v_pk_fma_f32 v[206:207], v[132:133], v[210:211], v[192:193] neg_lo:[0,0,1] neg_hi:[0,0,1]
	v_pk_mul_f32 v[192:193], v[136:137], v[210:211]
	v_pk_fma_f32 v[196:197], v[130:131], v[196:197], v[194:195]
	v_pk_mul_f32 v[194:195], v[176:177], v[212:213] op_sel_hi:[0,1]
	v_pk_mul_f32 v[214:215], v[176:177], v[178:179] op_sel_hi:[0,1]
	v_pk_mul_f32 v[224:225], v[38:39], v[216:217]
	v_pk_fma_f32 v[200:201], v[132:133], v[204:205], v[192:193]
	v_pk_mul_f32 v[192:193], v[176:177], v[202:203] op_sel_hi:[0,1]
	v_pk_mul_f32 v[210:211], v[176:177], v[208:209] op_sel_hi:[0,1]
	v_pk_mul_f32 v[220:221], v[176:177], v[196:197] op_sel_hi:[0,1]
	v_pk_mul_f32 v[222:223], v[40:41], v[214:215]
	v_pk_fma_f32 v[224:225], v[46:47], v[194:195], v[224:225] neg_lo:[0,0,1] neg_hi:[0,0,1]
	v_pk_mul_f32 v[194:195], v[38:39], v[194:195]
	v_pk_mul_f32 v[204:205], v[176:177], v[206:207] op_sel_hi:[0,1]
	v_pk_mul_f32 v[218:219], v[176:177], v[200:201] op_sel_hi:[0,1]
	v_pk_fma_f32 v[222:223], v[48:49], v[192:193], v[222:223] neg_lo:[0,0,1] neg_hi:[0,0,1]
	v_pk_mul_f32 v[228:229], v[34:35], v[220:221]
	v_pk_mul_f32 v[192:193], v[40:41], v[192:193]
	v_pk_fma_f32 v[216:217], v[46:47], v[216:217], v[194:195]
	v_pk_mul_f32 v[194:195], v[34:35], v[210:211]
	v_pk_mul_f32 v[226:227], v[36:37], v[218:219]
	v_pk_fma_f32 v[228:229], v[42:43], v[210:211], v[228:229] neg_lo:[0,0,1] neg_hi:[0,0,1]
	v_pk_fma_f32 v[214:215], v[48:49], v[214:215], v[192:193]
	v_pk_mul_f32 v[192:193], v[36:37], v[204:205]
	v_pk_fma_f32 v[210:211], v[42:43], v[220:221], v[194:195]
	v_add_co_u32_e32 v220, vcc, s88, v174
	v_pk_fma_f32 v[226:227], v[44:45], v[204:205], v[226:227] neg_lo:[0,0,1] neg_hi:[0,0,1]
	v_pk_fma_f32 v[204:205], v[44:45], v[218:219], v[192:193]
	v_cvt_pk_bf16_f32 v192, v224, v225
	v_cvt_pk_bf16_f32 v193, v222, v223
	v_cvt_pk_bf16_f32 v194, v228, v229
	v_cvt_pk_bf16_f32 v195, v226, v227
	v_addc_co_u32_e32 v221, vcc, 0, v175, vcc
	v_lshl_add_u64 v[218:219], v[174:175], 0, s[18:19]
	global_store_dwordx4 v[220:221], v[192:195], off
	s_nop 1
	v_cvt_pk_bf16_f32 v192, v216, v217
	v_cvt_pk_bf16_f32 v193, v214, v215
	v_cvt_pk_bf16_f32 v194, v210, v211
	v_cvt_pk_bf16_f32 v195, v204, v205
	global_store_dwordx4 v[218:219], v[192:195], off offset:128
	s_nop 1
	v_pk_mul_f32 v[194:195], v[142:143], v[198:199]
; __device__ __forceinline__ unsigned cvt_pk_bf16(float lo, float hi) { unsigned r; asm volatile("v_cvt_pk_bf16_f32 %0, %1, %2" : "=v"(r) : "v"(lo), "v"(hi)); return r; }
;     __device__ __forceinline__ void operator()(const f32x4 (&acc)[2][2][4][2], const pg8::Unit& u, int wr, int wc, int fr, int fq) const {
;     ...
;             for (int k = 0; k < 12; ++k) {
;                 if (k < 4 || k >= 8) {
;                     const int ai = k >> 3, m = k & 3;
;                     const int row = row0 + ai * 128 + m * 16;
;                     const f32x4 c0 = c[0] * osc, c1 = c[1] * osc, s0 = sn[0] * osc, s1 = sn[1] * osc;
;                     const f32x4 a0 = acc[ai][0][m][0], a1 = acc[ai][0][m][1], b0 = acc[ai][1][m][0], b1 = acc[ai][1][m][1];
;                     const f32x4 o10 = a0 * c0 - b0 * s0, o11 = a1 * c1 - b1 * s1, o20 = a0 * s0 + b0 * c0, o21 = a1 * s1 + b1 * c1;
;                     bf16_t* rowp = base + (size_t)row * 512 + col0;
;                     u32x4 w; w.x = cvt_pk_bf16(o10[0], o10[1]); w.y = cvt_pk_bf16(o10[2], o10[3]); w.z = cvt_pk_bf16(o11[0], o11[1]); w.w = cvt_pk_bf16(o11[2], o11[3]);
;                     *(u32x4*)(rowp) = w;
;                     w.x = cvt_pk_bf16(o20[0], o20[1]); w.y = cvt_pk_bf16(o20[2], o20[3]); w.z = cvt_pk_bf16(o21[0], o21[1]); w.w = cvt_pk_bf16(o21[2], o21[3]);
;                     *(u32x4*)(rowp + 64) = w;
;                 }
;                 if (k < 11) {
; #pragma unroll
;                     for (int e = 0; e < 2; ++e) { const f32x4 cn = c[e] * c16[e] - sn[e] * s16[e]; sn[e] = sn[e] * c16[e] + c[e] * s16[e]; c[e] = cn; } }
;             }
	v_pk_mul_f32 v[192:193], v[144:145], v[178:179]
	v_pk_fma_f32 v[210:211], v[138:139], v[212:213], v[194:195] neg_lo:[0,0,1] neg_hi:[0,0,1]
	v_pk_mul_f32 v[194:195], v[142:143], v[212:213]
	v_pk_fma_f32 v[204:205], v[140:141], v[202:203], v[192:193] neg_lo:[0,0,1] neg_hi:[0,0,1]
	v_pk_mul_f32 v[192:193], v[144:145], v[202:203]
	v_pk_fma_f32 v[198:199], v[138:139], v[198:199], v[194:195]
	v_pk_mul_f32 v[194:195], v[134:135], v[196:197]
	v_pk_fma_f32 v[178:179], v[140:141], v[178:179], v[192:193]
	v_pk_mul_f32 v[192:193], v[136:137], v[200:201]
	v_pk_fma_f32 v[212:213], v[130:131], v[208:209], v[194:195] neg_lo:[0,0,1] neg_hi:[0,0,1]
	v_pk_mul_f32 v[194:195], v[134:135], v[208:209]
	v_pk_mul_f32 v[216:217], v[176:177], v[198:199] op_sel_hi:[0,1]
	v_pk_fma_f32 v[202:203], v[132:133], v[206:207], v[192:193] neg_lo:[0,0,1] neg_hi:[0,0,1]
	v_pk_mul_f32 v[192:193], v[136:137], v[206:207]
	v_pk_fma_f32 v[196:197], v[130:131], v[196:197], v[194:195]
	v_pk_mul_f32 v[194:195], v[176:177], v[210:211] op_sel_hi:[0,1]
	v_pk_mul_f32 v[214:215], v[176:177], v[178:179] op_sel_hi:[0,1]
	v_pk_mul_f32 v[224:225], v[22:23], v[216:217]
	v_pk_fma_f32 v[200:201], v[132:133], v[200:201], v[192:193]
	v_pk_mul_f32 v[192:193], v[176:177], v[204:205] op_sel_hi:[0,1]
	v_pk_mul_f32 v[208:209], v[176:177], v[212:213] op_sel_hi:[0,1]
	v_pk_mul_f32 v[220:221], v[176:177], v[196:197] op_sel_hi:[0,1]
	v_pk_mul_f32 v[222:223], v[24:25], v[214:215]
	v_pk_fma_f32 v[224:225], v[30:31], v[194:195], v[224:225] neg_lo:[0,0,1] neg_hi:[0,0,1]
	v_pk_mul_f32 v[194:195], v[22:23], v[194:195]
	v_pk_mul_f32 v[206:207], v[176:177], v[202:203] op_sel_hi:[0,1]
	v_pk_mul_f32 v[218:219], v[176:177], v[200:201] op_sel_hi:[0,1]
	v_pk_fma_f32 v[222:223], v[32:33], v[192:193], v[222:223] neg_lo:[0,0,1] neg_hi:[0,0,1]
	v_pk_mul_f32 v[228:229], v[18:19], v[220:221]
	v_pk_mul_f32 v[192:193], v[24:25], v[192:193]
	v_pk_fma_f32 v[216:217], v[30:31], v[216:217], v[194:195]
	v_pk_mul_f32 v[194:195], v[18:19], v[208:209]
	v_pk_mul_f32 v[226:227], v[20:21], v[218:219]
	v_pk_fma_f32 v[228:229], v[26:27], v[208:209], v[228:229] neg_lo:[0,0,1] neg_hi:[0,0,1]
	v_pk_fma_f32 v[214:215], v[32:33], v[214:215], v[192:193]
	v_pk_mul_f32 v[192:193], v[20:21], v[206:207]
	v_pk_fma_f32 v[208:209], v[26:27], v[220:221], v[194:195]
	v_add_co_u32_e32 v220, vcc, s89, v174
	v_pk_fma_f32 v[226:227], v[28:29], v[206:207], v[226:227] neg_lo:[0,0,1] neg_hi:[0,0,1]
	v_pk_fma_f32 v[206:207], v[28:29], v[218:219], v[192:193]
	v_cvt_pk_bf16_f32 v192, v224, v225
	v_cvt_pk_bf16_f32 v193, v222, v223
	v_cvt_pk_bf16_f32 v194, v228, v229
	v_cvt_pk_bf16_f32 v195, v226, v227
	v_addc_co_u32_e32 v221, vcc, 0, v175, vcc
	v_lshl_add_u64 v[218:219], v[174:175], 0, s[20:21]
	global_store_dwordx4 v[220:221], v[192:195], off
	s_nop 1
	v_cvt_pk_bf16_f32 v192, v216, v217
	v_cvt_pk_bf16_f32 v193, v214, v215
	v_cvt_pk_bf16_f32 v194, v208, v209
	v_cvt_pk_bf16_f32 v195, v206, v207
	global_store_dwordx4 v[218:219], v[192:195], off offset:128
	s_nop 1
	v_pk_mul_f32 v[192:193], v[144:145], v[178:179]
	v_pk_mul_f32 v[194:195], v[142:143], v[198:199]
	v_pk_mul_f32 v[144:145], v[144:145], v[204:205]
	v_pk_mul_f32 v[142:143], v[142:143], v[210:211]
	v_pk_fma_f32 v[192:193], v[140:141], v[204:205], v[192:193] neg_lo:[0,0,1] neg_hi:[0,0,1]
	v_pk_fma_f32 v[194:195], v[138:139], v[210:211], v[194:195] neg_lo:[0,0,1] neg_hi:[0,0,1]
	v_pk_fma_f32 v[140:141], v[140:141], v[178:179], v[144:145]
	v_pk_fma_f32 v[138:139], v[138:139], v[198:199], v[142:143]
	v_pk_mul_f32 v[142:143], v[136:137], v[200:201]
	v_pk_mul_f32 v[144:145], v[134:135], v[196:197]
	v_pk_mul_f32 v[136:137], v[136:137], v[202:203]
	v_pk_mul_f32 v[134:135], v[134:135], v[212:213]
	v_pk_fma_f32 v[142:143], v[132:133], v[202:203], v[142:143] neg_lo:[0,0,1] neg_hi:[0,0,1]
	v_pk_fma_f32 v[144:145], v[130:131], v[212:213], v[144:145] neg_lo:[0,0,1] neg_hi:[0,0,1]
	v_pk_fma_f32 v[132:133], v[132:133], v[200:201], v[136:137]
	v_pk_fma_f32 v[130:131], v[130:131], v[196:197], v[134:135]
	v_pk_mul_f32 v[140:141], v[176:177], v[140:141] op_sel_hi:[0,1]
	v_pk_mul_f32 v[138:139], v[176:177], v[138:139] op_sel_hi:[0,1]
	v_pk_mul_f32 v[134:135], v[176:177], v[192:193] op_sel_hi:[0,1]
	v_pk_mul_f32 v[136:137], v[176:177], v[194:195] op_sel_hi:[0,1]
	v_pk_mul_f32 v[142:143], v[176:177], v[142:143] op_sel_hi:[0,1]
	v_pk_mul_f32 v[144:145], v[176:177], v[144:145] op_sel_hi:[0,1]
	v_pk_mul_f32 v[132:133], v[176:177], v[132:133] op_sel_hi:[0,1]
	v_pk_mul_f32 v[130:131], v[176:177], v[130:131] op_sel_hi:[0,1]
	v_pk_mul_f32 v[176:177], v[8:9], v[140:141]
	v_pk_mul_f32 v[178:179], v[6:7], v[138:139]
	v_pk_fma_f32 v[176:177], v[16:17], v[134:135], v[176:177] neg_lo:[0,0,1] neg_hi:[0,0,1]
	v_pk_fma_f32 v[178:179], v[14:15], v[136:137], v[178:179] neg_lo:[0,0,1] neg_hi:[0,0,1]
	v_pk_mul_f32 v[194:195], v[2:3], v[130:131]
	v_pk_mul_f32 v[134:135], v[8:9], v[134:135]
	v_pk_mul_f32 v[136:137], v[6:7], v[136:137]
	v_pk_mul_f32 v[192:193], v[4:5], v[132:133]
	v_pk_fma_f32 v[194:195], v[10:11], v[144:145], v[194:195] neg_lo:[0,0,1] neg_hi:[0,0,1]
	v_pk_fma_f32 v[134:135], v[16:17], v[140:141], v[134:135]
	v_pk_fma_f32 v[136:137], v[14:15], v[138:139], v[136:137]
	v_pk_mul_f32 v[138:139], v[4:5], v[142:143]
	v_pk_mul_f32 v[140:141], v[2:3], v[144:145]
	v_add_co_u32_e32 v144, vcc, s90, v174
	v_pk_fma_f32 v[192:193], v[12:13], v[142:143], v[192:193] neg_lo:[0,0,1] neg_hi:[0,0,1]
	v_pk_fma_f32 v[138:139], v[12:13], v[132:133], v[138:139]
	v_pk_fma_f32 v[140:141], v[10:11], v[130:131], v[140:141]
	v_lshl_add_u64 v[142:143], v[174:175], 0, s[24:25]
	v_cvt_pk_bf16_f32 v130, v178, v179
	v_cvt_pk_bf16_f32 v131, v176, v177
	v_cvt_pk_bf16_f32 v132, v194, v195
	v_cvt_pk_bf16_f32 v133, v192, v193
	v_addc_co_u32_e32 v145, vcc, 0, v175, vcc
	global_store_dwordx4 v[144:145], v[130:133], off
	s_nop 1
	v_cvt_pk_bf16_f32 v130, v136, v137
	v_cvt_pk_bf16_f32 v131, v134, v135
	v_cvt_pk_bf16_f32 v132, v140, v141
	v_cvt_pk_bf16_f32 v133, v138, v139
	global_store_dwordx4 v[142:143], v[130:133], off offset:128

; __device__ __forceinline__ unsigned cvt_pk_bf16(float lo, float hi) { unsigned r; asm volatile("v_cvt_pk_bf16_f32 %0, %1, %2" : "=v"(r) : "v"(lo), "v"(hi)); return r; }
; #define PG8_STAGE(bufoff, gbase, voff) do { _Pragma("unroll") for (int _i = 0; _i < 2; ++_i) \
;         __builtin_amdgcn_global_load_lds((const unsigned*)((const char*)(gbase) + (voff)[_i]), (PG8_LAS unsigned*)(lds + (bufoff) + ldsw + _i * 8192), 16, 0, 0); } while (0)
; #define PG8_SCHED __builtin_amdgcn_sched_barrier(0)
; template <class Epi, class Sched, bool ALIGN_EPI = false, bool SP2 = false>
; __device__ __forceinline__ void gemm_phase(PG8_LAS unsigned char* lds, const Gemm g, const Sched& S, const Epi& E) {
;     ...
;             PG8_LDB(B0, 0, 0); PG8_LDB(B1, 0, 1); PG8_SCHED; PG8_LDA(At, 0, 0); PG8_STAGE(PG8_SA(1, 1), a1 + hstep, voffA);
;     __device__ __forceinline__ void operator()(const f32x4 (&acc)[2][2][4][2], const pg8::Unit& u, int wr, int wc, int fr, int fq) const {
;     ...
;             const float* gn = sec == 0 ? qg : kg; const float osc = sec == 0 ? 0.125f * LOG2E : 1.f;
;             f32x4 g[2][2];
; #pragma unroll
;             for (int bj = 0; bj < 2; ++bj)
; #pragma unroll
;                 for (int n = 0; n < 2; ++n) g[bj][n] = *(const f32x4*)(gn + 32 * bj + 8 * fq + 4 * n);
;             const int col0 = 256 * half + 64 * wc + 8 * fq;
; #pragma unroll
;             for (int ai = 0; ai < 2; ++ai)
; #pragma unroll
;                 for (int m = 0; m < 4; ++m) {
;                     float ss = 0.f;
; #pragma unroll
;                     for (int bj = 0; bj < 2; ++bj)
; #pragma unroll
;                         for (int n = 0; n < 2; ++n) { const f32x4 x = acc[ai][bj][m][n]; ss += (x[0] * x[0] + x[1] * x[1]) + (x[2] * x[2] + x[3] * x[3]); }
;                     ss = row4_sum(ss);
;                     const float r = rsqrtf(ss * (1.f / 64.f) + EPS) * osc;
;                     bf16_t* rowp = base + (size_t)(row0 + ai * 128 + m * 16) * 512 + col0;
; #pragma unroll
;                     for (int bj = 0; bj < 2; ++bj) { const f32x4 v0 = acc[ai][bj][m][0] * r * g[bj][0], v1 = acc[ai][bj][m][1] * r * g[bj][1];
;                         u32x4 w; w.x = cvt_pk_bf16(v0[0], v0[1]); w.y = cvt_pk_bf16(v0[2], v0[3]); w.z = cvt_pk_bf16(v1[0], v1[1]); w.w = cvt_pk_bf16(v1[2], v1[3]);
;                         *(u32x4*)(rowp + 32 * bj) = w; }
.LBB0_205:
	s_cmp_lt_u32 s46, 2
	s_cselect_b64 vcc, -1, 0
	s_and_b64 s[4:5], vcc, exec
	s_cselect_b32 s5, s53, s55
	s_cselect_b32 s4, s52, s54
	global_load_dwordx4 v[142:145], v187, s[4:5]
	global_load_dwordx4 v[138:141], v187, s[4:5] offset:16
	global_load_dwordx4 v[134:137], v187, s[4:5] offset:128
	global_load_dwordx4 v[130:133], v187, s[4:5] offset:144
	s_mov_b32 s4, 0x55555555
	s_mov_b32 s5, 0x55555555
	v_and_b32_e32 v218, 1, v172
	v_sub_u32_e32 v219, 0, v218
	v_and_b32_e32 v218, 0xfffffc40, v219
	v_mul_f32_e32 v176, v127, v127
	v_mul_f32_e32 v177, v129, v129
	v_mul_f32_e32 v179, v123, v123
	v_mul_f32_e32 v191, v125, v125
	v_mul_f32_e32 v192, v119, v119
	v_mul_f32_e32 v193, v121, v121
	v_ashrrev_i32_e32 v173, 31, v172
	v_fmac_f32_e32 v176, v126, v126
	v_fmac_f32_e32 v177, v128, v128
	v_fmac_f32_e32 v179, v122, v122
	v_fmac_f32_e32 v191, v124, v124
	v_mul_f32_e32 v194, v115, v115
	v_mul_f32_e32 v195, v117, v117
	v_fmac_f32_e32 v192, v118, v118
	v_fmac_f32_e32 v193, v120, v120
	v_lshlrev_b64 v[174:175], 10, v[172:173]
	v_add_f32_e32 v173, v176, v177
	v_add_f32_e32 v176, v179, v191
	v_fmac_f32_e32 v194, v114, v114
	v_fmac_f32_e32 v195, v116, v116
	v_add_f32_e32 v177, v192, v193
	v_add_f32_e32 v173, v173, v176
	v_add_f32_e32 v179, v194, v195
	v_add_f32_e32 v173, v173, v177
	v_add_f32_e32 v173, v173, v179
	v_mov_b32_e32 v176, v173
	s_nop 1
	v_permlane16_swap_b32_e32 v173, v176
	v_add_f32_e32 v173, v173, v176
	v_mov_b32_e32 v176, v173
	s_nop 1
	v_permlane32_swap_b32_e32 v173, v176
	v_add_f32_e32 v173, v173, v176
	v_fmamk_f32 v173, v173, 0x3c800000, v188
	v_cndmask_b32_e32 v178, 1.0, v190, vcc
	v_mul_f32_e32 v176, 0x4b800000, v173
	v_cmp_gt_f32_e32 vcc, s91, v173
	v_lshlrev_b32_e32 v154, 1, v182
	v_lshl_or_b32 v154, s27, 9, v154
	v_cndmask_b32_e32 v173, v173, v176, vcc
	v_rsq_f32_e32 v173, v173
	v_lshl_add_u64 v[176:177], s[48:49], 0, v[154:155]
	v_mul_f32_e32 v196, v111, v111
	v_mul_f32_e32 v197, v113, v113
	v_mul_f32_e32 v154, 0x45800000, v173
	v_cndmask_b32_e32 v154, v173, v154, vcc
	v_mul_f32_e32 v154, v178, v154
	v_pk_mul_f32 v[126:127], v[126:127], v[154:155] op_sel_hi:[1,0]
	v_pk_mul_f32 v[128:129], v[128:129], v[154:155] op_sel_hi:[1,0]
	v_pk_mul_f32 v[122:123], v[122:123], v[154:155] op_sel_hi:[1,0]
	v_pk_mul_f32 v[124:125], v[124:125], v[154:155] op_sel_hi:[1,0]
	v_pk_mul_f32 v[118:119], v[118:119], v[154:155] op_sel_hi:[1,0]
	v_pk_mul_f32 v[114:115], v[114:115], v[154:155] op_sel_hi:[1,0]
	v_pk_mul_f32 v[116:117], v[116:117], v[154:155] op_sel_hi:[1,0]
	v_mul_f32_e32 v198, v107, v107
	v_mul_f32_e32 v199, v109, v109
	v_lshl_add_u64 v[174:175], v[176:177], 0, v[174:175]
	v_fmac_f32_e32 v196, v110, v110
	v_fmac_f32_e32 v197, v112, v112
	v_fmac_f32_e32 v198, v106, v106
	v_fmac_f32_e32 v199, v108, v108
	v_add_f32_e32 v179, v196, v197
	v_pk_mul_f32 v[120:121], v[120:121], v[154:155] op_sel_hi:[1,0]
	s_waitcnt vmcnt(0)
	s_add_i32 m0, s47, 0xc000
	s_nop 0
	global_load_lds_dwordx4 v164, s[94:95]
	s_add_i32 m0, s47, 0xe000
	s_nop 0
	global_load_lds_dwordx4 v166, s[94:95]
	v_pk_mul_f32 v[128:129], v[144:145], v[128:129]
	v_pk_mul_f32 v[126:127], v[142:143], v[126:127]
	v_pk_mul_f32 v[124:125], v[140:141], v[124:125]
	v_pk_mul_f32 v[122:123], v[138:139], v[122:123]
	v_pk_mul_f32 v[118:119], v[134:135], v[118:119]
	v_pk_mul_f32 v[192:193], v[132:133], v[116:117]
	v_pk_mul_f32 v[194:195], v[130:131], v[114:115]
	v_cvt_pk_bf16_f32 v114, v126, v127
	v_cvt_pk_bf16_f32 v115, v128, v129
	v_cvt_pk_bf16_f32 v116, v122, v123
	v_cvt_pk_bf16_f32 v117, v124, v125
	v_mov_b32_e32 v200, v114
	v_mov_b32_e32 v201, v115
	v_mov_b32_e32 v202, v116
	v_mov_b32_e32 v203, v117
	v_lshl_add_u64 v[216:217], v[174:175], 0, v[218:219]
	v_pk_mul_f32 v[120:121], v[136:137], v[120:121]
	s_nop 0
	v_cvt_pk_bf16_f32 v114, v118, v119
	v_mul_f32_e32 v117, v103, v103
	v_mul_f32_e32 v118, v105, v105
	v_add_f32_e32 v116, v198, v199
	v_fmac_f32_e32 v117, v102, v102
	v_fmac_f32_e32 v118, v104, v104
	v_add_f32_e32 v116, v179, v116
	v_add_f32_e32 v117, v117, v118
	v_add_f32_e32 v116, v116, v117
	v_mul_f32_e32 v117, v99, v99
	v_mul_f32_e32 v118, v101, v101
	v_fmac_f32_e32 v117, v98, v98
	v_fmac_f32_e32 v118, v100, v100
	v_add_f32_e32 v117, v117, v118
	v_add_f32_e32 v116, v116, v117
	v_mov_b32_e32 v117, v116
	s_nop 1
	v_permlane16_swap_b32_e32 v116, v117
	v_add_f32_e32 v116, v116, v117
	v_mov_b32_e32 v117, v116
	s_nop 1
	v_permlane32_swap_b32_e32 v116, v117
	v_add_f32_e32 v116, v116, v117
	v_fmamk_f32 v116, v116, 0x3c800000, v188
	v_mul_f32_e32 v117, 0x4b800000, v116
	v_cmp_gt_f32_e32 vcc, s91, v116
	v_cvt_pk_bf16_f32 v115, v120, v121
	s_nop 1
	v_cndmask_b32_e32 v116, v116, v117, vcc
	v_rsq_f32_e32 v118, v116
	v_cvt_pk_bf16_f32 v116, v194, v195
	v_cvt_pk_bf16_f32 v117, v192, v193
	v_mov_b32_dpp v212, v200 quad_perm:[1,0,3,2] row_mask:0xf bank_mask:0xf
	v_mov_b32_dpp v213, v201 quad_perm:[1,0,3,2] row_mask:0xf bank_mask:0xf
	v_mov_b32_dpp v214, v202 quad_perm:[1,0,3,2] row_mask:0xf bank_mask:0xf
	v_mov_b32_dpp v215, v203 quad_perm:[1,0,3,2] row_mask:0xf bank_mask:0xf
	v_mov_b32_dpp v204, v114 quad_perm:[1,0,3,2] row_mask:0xf bank_mask:0xf
	v_mov_b32_dpp v205, v115 quad_perm:[1,0,3,2] row_mask:0xf bank_mask:0xf
	v_mov_b32_dpp v206, v116 quad_perm:[1,0,3,2] row_mask:0xf bank_mask:0xf
	v_mov_b32_dpp v207, v117 quad_perm:[1,0,3,2] row_mask:0xf bank_mask:0xf
	v_cndmask_b32_e64 v212, v114, v212, s[4:5]
	v_cndmask_b32_e64 v213, v115, v213, s[4:5]
	v_cndmask_b32_e64 v214, v116, v214, s[4:5]
	v_cndmask_b32_e64 v215, v117, v215, s[4:5]
	v_cndmask_b32_e64 v208, v204, v200, s[4:5]
	v_cndmask_b32_e64 v209, v205, v201, s[4:5]
	v_cndmask_b32_e64 v210, v206, v202, s[4:5]
	v_cndmask_b32_e64 v211, v207, v203, s[4:5]
; __device__ __forceinline__ unsigned cvt_pk_bf16(float lo, float hi) { unsigned r; asm volatile("v_cvt_pk_bf16_f32 %0, %1, %2" : "=v"(r) : "v"(lo), "v"(hi)); return r; }
;     __device__ __forceinline__ void operator()(const f32x4 (&acc)[2][2][4][2], const pg8::Unit& u, int wr, int wc, int fr, int fq) const {
;     ...
;                 for (int m = 0; m < 4; ++m) {
;                     float ss = 0.f;
; #pragma unroll
;                     for (int bj = 0; bj < 2; ++bj)
; #pragma unroll
;                         for (int n = 0; n < 2; ++n) { const f32x4 x = acc[ai][bj][m][n]; ss += (x[0] * x[0] + x[1] * x[1]) + (x[2] * x[2] + x[3] * x[3]); }
;                     ss = row4_sum(ss);
;                     const float r = rsqrtf(ss * (1.f / 64.f) + EPS) * osc;
;                     bf16_t* rowp = base + (size_t)(row0 + ai * 128 + m * 16) * 512 + col0;
; #pragma unroll
;                     for (int bj = 0; bj < 2; ++bj) { const f32x4 v0 = acc[ai][bj][m][0] * r * g[bj][0], v1 = acc[ai][bj][m][1] * r * g[bj][1];
;                         u32x4 w; w.x = cvt_pk_bf16(v0[0], v0[1]); w.y = cvt_pk_bf16(v0[2], v0[3]); w.z = cvt_pk_bf16(v1[0], v1[1]); w.w = cvt_pk_bf16(v1[2], v1[3]);
;                         *(u32x4*)(rowp + 32 * bj) = w; }
;                 }
	global_store_dwordx4 v[216:217], v[208:211], off
	global_store_dwordx4 v[216:217], v[212:215], off offset:1024
	s_nop 1
	v_mul_f32_e32 v114, 0x45800000, v118
	v_cndmask_b32_e32 v114, v118, v114, vcc
	v_or_b32_e32 v116, 16, v172
	v_mul_f32_e32 v114, v178, v114
	v_ashrrev_i32_e32 v117, 31, v116
	v_lshlrev_b64 v[116:117], 10, v[116:117]
	v_pk_mul_f32 v[110:111], v[110:111], v[114:115] op_sel_hi:[1,0]
	v_pk_mul_f32 v[112:113], v[112:113], v[114:115] op_sel_hi:[1,0]
	v_pk_mul_f32 v[106:107], v[106:107], v[114:115] op_sel_hi:[1,0]
	v_pk_mul_f32 v[108:109], v[108:109], v[114:115] op_sel_hi:[1,0]
	v_pk_mul_f32 v[102:103], v[102:103], v[114:115] op_sel_hi:[1,0]
	v_lshl_add_u64 v[116:117], v[176:177], 0, v[116:117]
	v_pk_mul_f32 v[112:113], v[144:145], v[112:113]
	v_pk_mul_f32 v[110:111], v[142:143], v[110:111]
	v_pk_mul_f32 v[118:119], v[140:141], v[108:109]
	v_pk_mul_f32 v[108:109], v[138:139], v[106:107]
	v_cvt_pk_bf16_f32 v106, v110, v111
	v_cvt_pk_bf16_f32 v107, v112, v113
	v_pk_mul_f32 v[102:103], v[134:135], v[102:103]
	v_pk_mul_f32 v[98:99], v[98:99], v[114:115] op_sel_hi:[1,0]
	v_pk_mul_f32 v[100:101], v[100:101], v[114:115] op_sel_hi:[1,0]
	v_cvt_pk_bf16_f32 v108, v108, v109
	v_cvt_pk_bf16_f32 v109, v118, v119
	v_mov_b32_e32 v200, v106
	v_mov_b32_e32 v201, v107
	v_mov_b32_e32 v202, v108
	v_mov_b32_e32 v203, v109
	v_lshl_add_u64 v[216:217], v[116:117], 0, v[218:219]
	v_pk_mul_f32 v[104:105], v[104:105], v[114:115] op_sel_hi:[1,0]
	s_nop 0
	v_pk_mul_f32 v[106:107], v[132:133], v[100:101]
	v_pk_mul_f32 v[100:101], v[130:131], v[98:99]
	v_cvt_pk_bf16_f32 v98, v102, v103
	v_mul_f32_e32 v102, v95, v95
	v_mul_f32_e32 v103, v97, v97
	v_pk_mul_f32 v[104:105], v[136:137], v[104:105]
	v_fmac_f32_e32 v102, v94, v94
	v_fmac_f32_e32 v103, v96, v96
	v_cvt_pk_bf16_f32 v99, v104, v105
	v_add_f32_e32 v102, v102, v103
	v_mul_f32_e32 v103, v91, v91
	v_mul_f32_e32 v104, v93, v93
	v_fmac_f32_e32 v103, v90, v90
	v_fmac_f32_e32 v104, v92, v92
	v_add_f32_e32 v103, v103, v104
	v_add_f32_e32 v102, v102, v103
	v_mul_f32_e32 v103, v87, v87
	v_mul_f32_e32 v104, v89, v89
	v_fmac_f32_e32 v103, v86, v86
	v_fmac_f32_e32 v104, v88, v88
	v_add_f32_e32 v103, v103, v104
	v_add_f32_e32 v102, v102, v103
	v_mul_f32_e32 v103, v83, v83
	v_mul_f32_e32 v104, v85, v85
	v_fmac_f32_e32 v103, v82, v82
	v_fmac_f32_e32 v104, v84, v84
	v_add_f32_e32 v103, v103, v104
	v_add_f32_e32 v102, v102, v103
	v_mov_b32_e32 v103, v102
	s_nop 1
	v_permlane16_swap_b32_e32 v102, v103
	v_add_f32_e32 v102, v102, v103
	v_mov_b32_e32 v103, v102
	s_nop 1
	v_permlane32_swap_b32_e32 v102, v103
	v_add_f32_e32 v102, v102, v103
	v_fmamk_f32 v102, v102, 0x3c800000, v188
	v_mul_f32_e32 v103, 0x4b800000, v102
	v_cmp_gt_f32_e32 vcc, s91, v102
	v_cvt_pk_bf16_f32 v100, v100, v101
	v_cvt_pk_bf16_f32 v101, v106, v107
	v_mov_b32_dpp v212, v200 quad_perm:[1,0,3,2] row_mask:0xf bank_mask:0xf
	v_mov_b32_dpp v213, v201 quad_perm:[1,0,3,2] row_mask:0xf bank_mask:0xf
	v_mov_b32_dpp v214, v202 quad_perm:[1,0,3,2] row_mask:0xf bank_mask:0xf
	v_mov_b32_dpp v215, v203 quad_perm:[1,0,3,2] row_mask:0xf bank_mask:0xf
	v_mov_b32_dpp v204, v98 quad_perm:[1,0,3,2] row_mask:0xf bank_mask:0xf
	v_mov_b32_dpp v205, v99 quad_perm:[1,0,3,2] row_mask:0xf bank_mask:0xf
	v_mov_b32_dpp v206, v100 quad_perm:[1,0,3,2] row_mask:0xf bank_mask:0xf
	v_mov_b32_dpp v207, v101 quad_perm:[1,0,3,2] row_mask:0xf bank_mask:0xf
	v_cndmask_b32_e64 v212, v98, v212, s[4:5]
	v_cndmask_b32_e64 v213, v99, v213, s[4:5]
	v_cndmask_b32_e64 v214, v100, v214, s[4:5]
	v_cndmask_b32_e64 v215, v101, v215, s[4:5]
	v_cndmask_b32_e64 v208, v204, v200, s[4:5]
	v_cndmask_b32_e64 v209, v205, v201, s[4:5]
	v_cndmask_b32_e64 v210, v206, v202, s[4:5]
	v_cndmask_b32_e64 v211, v207, v203, s[4:5]
	global_store_dwordx4 v[216:217], v[208:211], off
	global_store_dwordx4 v[216:217], v[212:215], off offset:1024
	s_nop 0
	v_cndmask_b32_e32 v102, v102, v103, vcc
	v_rsq_f32_e32 v102, v102
	v_or_b32_e32 v100, 32, v172
	v_ashrrev_i32_e32 v101, 31, v100
	v_lshlrev_b64 v[100:101], 10, v[100:101]
	v_mul_f32_e32 v98, 0x45800000, v102
	v_cndmask_b32_e32 v98, v102, v98, vcc
	v_mul_f32_e32 v98, v178, v98
	v_pk_mul_f32 v[94:95], v[94:95], v[98:99] op_sel_hi:[1,0]
	v_pk_mul_f32 v[96:97], v[96:97], v[98:99] op_sel_hi:[1,0]
	v_pk_mul_f32 v[90:91], v[90:91], v[98:99] op_sel_hi:[1,0]
	v_pk_mul_f32 v[92:93], v[92:93], v[98:99] op_sel_hi:[1,0]
	v_pk_mul_f32 v[86:87], v[86:87], v[98:99] op_sel_hi:[1,0]
	v_lshl_add_u64 v[100:101], v[176:177], 0, v[100:101]
	v_pk_mul_f32 v[96:97], v[144:145], v[96:97]
	v_pk_mul_f32 v[94:95], v[142:143], v[94:95]
	v_pk_mul_f32 v[102:103], v[140:141], v[92:93]
	v_pk_mul_f32 v[92:93], v[138:139], v[90:91]
	v_cvt_pk_bf16_f32 v90, v94, v95
	v_cvt_pk_bf16_f32 v91, v96, v97
	v_pk_mul_f32 v[86:87], v[134:135], v[86:87]
	v_pk_mul_f32 v[82:83], v[82:83], v[98:99] op_sel_hi:[1,0]
	v_pk_mul_f32 v[84:85], v[84:85], v[98:99] op_sel_hi:[1,0]
	v_cvt_pk_bf16_f32 v92, v92, v93
	v_cvt_pk_bf16_f32 v93, v102, v103
	v_mov_b32_e32 v200, v90
	v_mov_b32_e32 v201, v91
	v_mov_b32_e32 v202, v92
	v_mov_b32_e32 v203, v93
	v_lshl_add_u64 v[216:217], v[100:101], 0, v[218:219]
	v_pk_mul_f32 v[88:89], v[88:89], v[98:99] op_sel_hi:[1,0]
	s_nop 0
	v_pk_mul_f32 v[90:91], v[132:133], v[84:85]
	v_pk_mul_f32 v[84:85], v[130:131], v[82:83]
	v_cvt_pk_bf16_f32 v82, v86, v87
	v_mul_f32_e32 v86, v79, v79
	v_mul_f32_e32 v87, v81, v81
	v_pk_mul_f32 v[88:89], v[136:137], v[88:89]
	v_fmac_f32_e32 v86, v78, v78
	v_fmac_f32_e32 v87, v80, v80
	v_cvt_pk_bf16_f32 v83, v88, v89
	v_add_f32_e32 v86, v86, v87
	v_mul_f32_e32 v87, v75, v75
	v_mul_f32_e32 v88, v77, v77
	v_fmac_f32_e32 v87, v74, v74
	v_fmac_f32_e32 v88, v76, v76
; __device__ __forceinline__ unsigned cvt_pk_bf16(float lo, float hi) { unsigned r; asm volatile("v_cvt_pk_bf16_f32 %0, %1, %2" : "=v"(r) : "v"(lo), "v"(hi)); return r; }
;     __device__ __forceinline__ void operator()(const f32x4 (&acc)[2][2][4][2], const pg8::Unit& u, int wr, int wc, int fr, int fq) const {
;     ...
;                 for (int m = 0; m < 4; ++m) {
;                     float ss = 0.f;
; #pragma unroll
;                     for (int bj = 0; bj < 2; ++bj)
; #pragma unroll
;                         for (int n = 0; n < 2; ++n) { const f32x4 x = acc[ai][bj][m][n]; ss += (x[0] * x[0] + x[1] * x[1]) + (x[2] * x[2] + x[3] * x[3]); }
;                     ss = row4_sum(ss);
;                     const float r = rsqrtf(ss * (1.f / 64.f) + EPS) * osc;
;                     bf16_t* rowp = base + (size_t)(row0 + ai * 128 + m * 16) * 512 + col0;
; #pragma unroll
;                     for (int bj = 0; bj < 2; ++bj) { const f32x4 v0 = acc[ai][bj][m][0] * r * g[bj][0], v1 = acc[ai][bj][m][1] * r * g[bj][1];
;                         u32x4 w; w.x = cvt_pk_bf16(v0[0], v0[1]); w.y = cvt_pk_bf16(v0[2], v0[3]); w.z = cvt_pk_bf16(v1[0], v1[1]); w.w = cvt_pk_bf16(v1[2], v1[3]);
;                         *(u32x4*)(rowp + 32 * bj) = w; }
;                 }
	v_add_f32_e32 v87, v87, v88
	v_add_f32_e32 v86, v86, v87
	v_mul_f32_e32 v87, v71, v71
	v_mul_f32_e32 v88, v73, v73
	v_fmac_f32_e32 v87, v70, v70
	v_fmac_f32_e32 v88, v72, v72
	v_add_f32_e32 v87, v87, v88
	v_add_f32_e32 v86, v86, v87
	v_mul_f32_e32 v87, v67, v67
	v_mul_f32_e32 v88, v69, v69
	v_fmac_f32_e32 v87, v66, v66
	v_fmac_f32_e32 v88, v68, v68
	v_add_f32_e32 v87, v87, v88
	v_add_f32_e32 v86, v86, v87
	v_mov_b32_e32 v87, v86
	s_nop 1
	v_permlane16_swap_b32_e32 v86, v87
	v_add_f32_e32 v86, v86, v87
	v_mov_b32_e32 v87, v86
	s_nop 1
	v_permlane32_swap_b32_e32 v86, v87
	v_add_f32_e32 v86, v86, v87
	v_fmamk_f32 v86, v86, 0x3c800000, v188
	v_mul_f32_e32 v87, 0x4b800000, v86
	v_cmp_gt_f32_e32 vcc, s91, v86
	v_cvt_pk_bf16_f32 v84, v84, v85
	v_cvt_pk_bf16_f32 v85, v90, v91
	v_mov_b32_dpp v212, v200 quad_perm:[1,0,3,2] row_mask:0xf bank_mask:0xf
	v_mov_b32_dpp v213, v201 quad_perm:[1,0,3,2] row_mask:0xf bank_mask:0xf
	v_mov_b32_dpp v214, v202 quad_perm:[1,0,3,2] row_mask:0xf bank_mask:0xf
	v_mov_b32_dpp v215, v203 quad_perm:[1,0,3,2] row_mask:0xf bank_mask:0xf
	v_mov_b32_dpp v204, v82 quad_perm:[1,0,3,2] row_mask:0xf bank_mask:0xf
	v_mov_b32_dpp v205, v83 quad_perm:[1,0,3,2] row_mask:0xf bank_mask:0xf
	v_mov_b32_dpp v206, v84 quad_perm:[1,0,3,2] row_mask:0xf bank_mask:0xf
	v_mov_b32_dpp v207, v85 quad_perm:[1,0,3,2] row_mask:0xf bank_mask:0xf
	v_cndmask_b32_e64 v212, v82, v212, s[4:5]
	v_cndmask_b32_e64 v213, v83, v213, s[4:5]
	v_cndmask_b32_e64 v214, v84, v214, s[4:5]
	v_cndmask_b32_e64 v215, v85, v215, s[4:5]
	v_cndmask_b32_e64 v208, v204, v200, s[4:5]
	v_cndmask_b32_e64 v209, v205, v201, s[4:5]
	v_cndmask_b32_e64 v210, v206, v202, s[4:5]
	v_cndmask_b32_e64 v211, v207, v203, s[4:5]
	global_store_dwordx4 v[216:217], v[208:211], off
	global_store_dwordx4 v[216:217], v[212:215], off offset:1024
	s_nop 0
	v_cndmask_b32_e32 v86, v86, v87, vcc
	v_rsq_f32_e32 v86, v86
	v_or_b32_e32 v84, 48, v172
	v_ashrrev_i32_e32 v85, 31, v84
	v_lshlrev_b64 v[84:85], 10, v[84:85]
	v_mul_f32_e32 v82, 0x45800000, v86
	v_cndmask_b32_e32 v82, v86, v82, vcc
	v_mul_f32_e32 v82, v178, v82
	v_pk_mul_f32 v[78:79], v[78:79], v[82:83] op_sel_hi:[1,0]
	v_pk_mul_f32 v[80:81], v[80:81], v[82:83] op_sel_hi:[1,0]
	v_pk_mul_f32 v[74:75], v[74:75], v[82:83] op_sel_hi:[1,0]
	v_pk_mul_f32 v[76:77], v[76:77], v[82:83] op_sel_hi:[1,0]
	v_pk_mul_f32 v[70:71], v[70:71], v[82:83] op_sel_hi:[1,0]
	v_lshl_add_u64 v[84:85], v[176:177], 0, v[84:85]
	v_pk_mul_f32 v[80:81], v[144:145], v[80:81]
	v_pk_mul_f32 v[78:79], v[142:143], v[78:79]
	v_pk_mul_f32 v[86:87], v[140:141], v[76:77]
	v_pk_mul_f32 v[76:77], v[138:139], v[74:75]
	v_cvt_pk_bf16_f32 v74, v78, v79
	v_cvt_pk_bf16_f32 v75, v80, v81
	v_pk_mul_f32 v[70:71], v[134:135], v[70:71]
	v_pk_mul_f32 v[66:67], v[66:67], v[82:83] op_sel_hi:[1,0]
	v_pk_mul_f32 v[68:69], v[68:69], v[82:83] op_sel_hi:[1,0]
	v_cvt_pk_bf16_f32 v76, v76, v77
	v_cvt_pk_bf16_f32 v77, v86, v87
	v_mov_b32_e32 v200, v74
	v_mov_b32_e32 v201, v75
	v_mov_b32_e32 v202, v76
	v_mov_b32_e32 v203, v77
	v_lshl_add_u64 v[216:217], v[84:85], 0, v[218:219]
	v_pk_mul_f32 v[72:73], v[72:73], v[82:83] op_sel_hi:[1,0]
	s_nop 0
	v_pk_mul_f32 v[74:75], v[132:133], v[68:69]
	v_pk_mul_f32 v[68:69], v[130:131], v[66:67]
	v_cvt_pk_bf16_f32 v66, v70, v71
	v_mul_f32_e32 v70, v63, v63
	v_mul_f32_e32 v71, v65, v65
	v_pk_mul_f32 v[72:73], v[136:137], v[72:73]
	v_fmac_f32_e32 v70, v62, v62
	v_fmac_f32_e32 v71, v64, v64
	v_cvt_pk_bf16_f32 v67, v72, v73
	v_add_f32_e32 v70, v70, v71
	v_mul_f32_e32 v71, v59, v59
	v_mul_f32_e32 v72, v61, v61
	v_fmac_f32_e32 v71, v58, v58
	v_fmac_f32_e32 v72, v60, v60
	v_add_f32_e32 v71, v71, v72
	v_add_f32_e32 v70, v70, v71
	v_mul_f32_e32 v71, v55, v55
	v_mul_f32_e32 v72, v57, v57
	v_fmac_f32_e32 v71, v54, v54
	v_fmac_f32_e32 v72, v56, v56
	v_add_f32_e32 v71, v71, v72
	v_add_f32_e32 v70, v70, v71
	v_mul_f32_e32 v71, v51, v51
	v_mul_f32_e32 v72, v53, v53
	v_fmac_f32_e32 v71, v50, v50
	v_fmac_f32_e32 v72, v52, v52
	v_add_f32_e32 v71, v71, v72
	v_add_f32_e32 v70, v70, v71
	v_mov_b32_e32 v71, v70
	s_nop 1
	v_permlane16_swap_b32_e32 v70, v71
	v_add_f32_e32 v70, v70, v71
	v_mov_b32_e32 v71, v70
	s_nop 1
	v_permlane32_swap_b32_e32 v70, v71
	v_add_f32_e32 v70, v70, v71
	v_fmamk_f32 v70, v70, 0x3c800000, v188
	v_mul_f32_e32 v71, 0x4b800000, v70
	v_cmp_gt_f32_e32 vcc, s91, v70
	v_cvt_pk_bf16_f32 v68, v68, v69
	v_cvt_pk_bf16_f32 v69, v74, v75
	v_mov_b32_dpp v212, v200 quad_perm:[1,0,3,2] row_mask:0xf bank_mask:0xf
	v_mov_b32_dpp v213, v201 quad_perm:[1,0,3,2] row_mask:0xf bank_mask:0xf
	v_mov_b32_dpp v214, v202 quad_perm:[1,0,3,2] row_mask:0xf bank_mask:0xf
	v_mov_b32_dpp v215, v203 quad_perm:[1,0,3,2] row_mask:0xf bank_mask:0xf
	v_mov_b32_dpp v204, v66 quad_perm:[1,0,3,2] row_mask:0xf bank_mask:0xf
	v_mov_b32_dpp v205, v67 quad_perm:[1,0,3,2] row_mask:0xf bank_mask:0xf
	v_mov_b32_dpp v206, v68 quad_perm:[1,0,3,2] row_mask:0xf bank_mask:0xf
	v_mov_b32_dpp v207, v69 quad_perm:[1,0,3,2] row_mask:0xf bank_mask:0xf
	v_cndmask_b32_e64 v212, v66, v212, s[4:5]
	v_cndmask_b32_e64 v213, v67, v213, s[4:5]
	v_cndmask_b32_e64 v214, v68, v214, s[4:5]
	v_cndmask_b32_e64 v215, v69, v215, s[4:5]
	v_cndmask_b32_e64 v208, v204, v200, s[4:5]
	v_cndmask_b32_e64 v209, v205, v201, s[4:5]
	v_cndmask_b32_e64 v210, v206, v202, s[4:5]
	v_cndmask_b32_e64 v211, v207, v203, s[4:5]
	global_store_dwordx4 v[216:217], v[208:211], off
	global_store_dwordx4 v[216:217], v[212:215], off offset:1024
	s_nop 0
	v_cndmask_b32_e32 v70, v70, v71, vcc
	v_rsq_f32_e32 v70, v70
	v_lshl_add_u64 v[68:69], v[174:175], 0, s[16:17]
	v_mul_f32_e32 v66, 0x45800000, v70
	v_cndmask_b32_e32 v66, v70, v66, vcc
	v_mul_f32_e32 v66, v178, v66
; __device__ __forceinline__ unsigned cvt_pk_bf16(float lo, float hi) { unsigned r; asm volatile("v_cvt_pk_bf16_f32 %0, %1, %2" : "=v"(r) : "v"(lo), "v"(hi)); return r; }
;     __device__ __forceinline__ void operator()(const f32x4 (&acc)[2][2][4][2], const pg8::Unit& u, int wr, int wc, int fr, int fq) const {
;     ...
;                 for (int m = 0; m < 4; ++m) {
;                     float ss = 0.f;
; #pragma unroll
;                     for (int bj = 0; bj < 2; ++bj)
; #pragma unroll
;                         for (int n = 0; n < 2; ++n) { const f32x4 x = acc[ai][bj][m][n]; ss += (x[0] * x[0] + x[1] * x[1]) + (x[2] * x[2] + x[3] * x[3]); }
;                     ss = row4_sum(ss);
;                     const float r = rsqrtf(ss * (1.f / 64.f) + EPS) * osc;
;                     bf16_t* rowp = base + (size_t)(row0 + ai * 128 + m * 16) * 512 + col0;
; #pragma unroll
;                     for (int bj = 0; bj < 2; ++bj) { const f32x4 v0 = acc[ai][bj][m][0] * r * g[bj][0], v1 = acc[ai][bj][m][1] * r * g[bj][1];
;                         u32x4 w; w.x = cvt_pk_bf16(v0[0], v0[1]); w.y = cvt_pk_bf16(v0[2], v0[3]); w.z = cvt_pk_bf16(v1[0], v1[1]); w.w = cvt_pk_bf16(v1[2], v1[3]);
;                         *(u32x4*)(rowp + 32 * bj) = w; }
;                 }
	v_pk_mul_f32 v[62:63], v[62:63], v[66:67] op_sel_hi:[1,0]
	v_pk_mul_f32 v[58:59], v[58:59], v[66:67] op_sel_hi:[1,0]
	v_pk_mul_f32 v[62:63], v[142:143], v[62:63]
	v_pk_mul_f32 v[60:61], v[60:61], v[66:67] op_sel_hi:[1,0]
	v_pk_mul_f32 v[64:65], v[64:65], v[66:67] op_sel_hi:[1,0]
	v_pk_mul_f32 v[70:71], v[140:141], v[60:61]
	v_pk_mul_f32 v[60:61], v[138:139], v[58:59]
	v_cvt_pk_bf16_f32 v58, v62, v63
	v_add_co_u32_e32 v62, vcc, s87, v174
	v_pk_mul_f32 v[54:55], v[54:55], v[66:67] op_sel_hi:[1,0]
	v_pk_mul_f32 v[64:65], v[144:145], v[64:65]
	v_addc_co_u32_e32 v63, vcc, 0, v175, vcc
	v_cvt_pk_bf16_f32 v59, v64, v65
	v_pk_mul_f32 v[54:55], v[134:135], v[54:55]
	v_pk_mul_f32 v[50:51], v[50:51], v[66:67] op_sel_hi:[1,0]
	v_pk_mul_f32 v[52:53], v[52:53], v[66:67] op_sel_hi:[1,0]
	v_cvt_pk_bf16_f32 v60, v60, v61
	v_cvt_pk_bf16_f32 v61, v70, v71
	v_mov_b32_e32 v200, v58
	v_mov_b32_e32 v201, v59
	v_mov_b32_e32 v202, v60
	v_mov_b32_e32 v203, v61
	v_lshl_add_u64 v[216:217], v[62:63], 0, v[218:219]
	v_pk_mul_f32 v[56:57], v[56:57], v[66:67] op_sel_hi:[1,0]
	s_nop 0
	v_pk_mul_f32 v[58:59], v[132:133], v[52:53]
	v_pk_mul_f32 v[52:53], v[130:131], v[50:51]
	v_cvt_pk_bf16_f32 v50, v54, v55
	v_mul_f32_e32 v54, v47, v47
	v_mul_f32_e32 v55, v49, v49
	v_pk_mul_f32 v[56:57], v[136:137], v[56:57]
	v_fmac_f32_e32 v54, v46, v46
	v_fmac_f32_e32 v55, v48, v48
	v_cvt_pk_bf16_f32 v51, v56, v57
	v_add_f32_e32 v54, v54, v55
	v_mul_f32_e32 v55, v43, v43
	v_mul_f32_e32 v56, v45, v45
	v_fmac_f32_e32 v55, v42, v42
	v_fmac_f32_e32 v56, v44, v44
	v_add_f32_e32 v55, v55, v56
	v_add_f32_e32 v54, v54, v55
	v_mul_f32_e32 v55, v39, v39
	v_mul_f32_e32 v56, v41, v41
	v_fmac_f32_e32 v55, v38, v38
	v_fmac_f32_e32 v56, v40, v40
	v_add_f32_e32 v55, v55, v56
	v_add_f32_e32 v54, v54, v55
	v_mul_f32_e32 v55, v35, v35
	v_mul_f32_e32 v56, v37, v37
	v_fmac_f32_e32 v55, v34, v34
	v_fmac_f32_e32 v56, v36, v36
	v_add_f32_e32 v55, v55, v56
	v_add_f32_e32 v54, v54, v55
	v_mov_b32_e32 v55, v54
	s_nop 1
	v_permlane16_swap_b32_e32 v54, v55
	v_add_f32_e32 v54, v54, v55
	v_mov_b32_e32 v55, v54
	s_nop 1
	v_permlane32_swap_b32_e32 v54, v55
	v_add_f32_e32 v54, v54, v55
	v_fmamk_f32 v54, v54, 0x3c800000, v188
	v_mul_f32_e32 v55, 0x4b800000, v54
	v_cmp_gt_f32_e32 vcc, s91, v54
	v_cvt_pk_bf16_f32 v52, v52, v53
	v_cvt_pk_bf16_f32 v53, v58, v59
	v_mov_b32_dpp v212, v200 quad_perm:[1,0,3,2] row_mask:0xf bank_mask:0xf
	v_mov_b32_dpp v213, v201 quad_perm:[1,0,3,2] row_mask:0xf bank_mask:0xf
	v_mov_b32_dpp v214, v202 quad_perm:[1,0,3,2] row_mask:0xf bank_mask:0xf
	v_mov_b32_dpp v215, v203 quad_perm:[1,0,3,2] row_mask:0xf bank_mask:0xf
	v_mov_b32_dpp v204, v50 quad_perm:[1,0,3,2] row_mask:0xf bank_mask:0xf
	v_mov_b32_dpp v205, v51 quad_perm:[1,0,3,2] row_mask:0xf bank_mask:0xf
	v_mov_b32_dpp v206, v52 quad_perm:[1,0,3,2] row_mask:0xf bank_mask:0xf
	v_mov_b32_dpp v207, v53 quad_perm:[1,0,3,2] row_mask:0xf bank_mask:0xf
	v_cndmask_b32_e64 v212, v50, v212, s[4:5]
	v_cndmask_b32_e64 v213, v51, v213, s[4:5]
	v_cndmask_b32_e64 v214, v52, v214, s[4:5]
	v_cndmask_b32_e64 v215, v53, v215, s[4:5]
	v_cndmask_b32_e64 v208, v204, v200, s[4:5]
	v_cndmask_b32_e64 v209, v205, v201, s[4:5]
	v_cndmask_b32_e64 v210, v206, v202, s[4:5]
	v_cndmask_b32_e64 v211, v207, v203, s[4:5]
	global_store_dwordx4 v[216:217], v[208:211], off
	global_store_dwordx4 v[216:217], v[212:215], off offset:1024
	s_nop 0
	v_cndmask_b32_e32 v54, v54, v55, vcc
	v_rsq_f32_e32 v54, v54
	v_lshl_add_u64 v[52:53], v[174:175], 0, s[18:19]
	v_mul_f32_e32 v50, 0x45800000, v54
	v_cndmask_b32_e32 v50, v54, v50, vcc
	v_mul_f32_e32 v50, v178, v50
	v_pk_mul_f32 v[46:47], v[46:47], v[50:51] op_sel_hi:[1,0]
	v_pk_mul_f32 v[42:43], v[42:43], v[50:51] op_sel_hi:[1,0]
	v_pk_mul_f32 v[46:47], v[142:143], v[46:47]
	v_pk_mul_f32 v[44:45], v[44:45], v[50:51] op_sel_hi:[1,0]
	v_pk_mul_f32 v[48:49], v[48:49], v[50:51] op_sel_hi:[1,0]
	v_pk_mul_f32 v[54:55], v[140:141], v[44:45]
	v_pk_mul_f32 v[44:45], v[138:139], v[42:43]
	v_cvt_pk_bf16_f32 v42, v46, v47
	v_add_co_u32_e32 v46, vcc, s88, v174
	v_pk_mul_f32 v[38:39], v[38:39], v[50:51] op_sel_hi:[1,0]
	v_pk_mul_f32 v[48:49], v[144:145], v[48:49]
	v_addc_co_u32_e32 v47, vcc, 0, v175, vcc
	v_cvt_pk_bf16_f32 v43, v48, v49
	v_pk_mul_f32 v[38:39], v[134:135], v[38:39]
	v_pk_mul_f32 v[34:35], v[34:35], v[50:51] op_sel_hi:[1,0]
	v_pk_mul_f32 v[36:37], v[36:37], v[50:51] op_sel_hi:[1,0]
	v_cvt_pk_bf16_f32 v44, v44, v45
	v_cvt_pk_bf16_f32 v45, v54, v55
	v_mov_b32_e32 v200, v42
	v_mov_b32_e32 v201, v43
	v_mov_b32_e32 v202, v44
	v_mov_b32_e32 v203, v45
	v_lshl_add_u64 v[216:217], v[46:47], 0, v[218:219]
	v_pk_mul_f32 v[40:41], v[40:41], v[50:51] op_sel_hi:[1,0]
	s_nop 0
	v_pk_mul_f32 v[42:43], v[132:133], v[36:37]
	v_pk_mul_f32 v[36:37], v[130:131], v[34:35]
	v_cvt_pk_bf16_f32 v34, v38, v39
	v_mul_f32_e32 v38, v31, v31
	v_mul_f32_e32 v39, v33, v33
	v_pk_mul_f32 v[40:41], v[136:137], v[40:41]
	v_fmac_f32_e32 v38, v30, v30
	v_fmac_f32_e32 v39, v32, v32
	v_cvt_pk_bf16_f32 v35, v40, v41
	v_add_f32_e32 v38, v38, v39
	v_mul_f32_e32 v39, v27, v27
	v_mul_f32_e32 v40, v29, v29
	v_fmac_f32_e32 v39, v26, v26
	v_fmac_f32_e32 v40, v28, v28
	v_add_f32_e32 v39, v39, v40
	v_add_f32_e32 v38, v38, v39
	v_mul_f32_e32 v39, v23, v23
	v_mul_f32_e32 v40, v25, v25
	v_fmac_f32_e32 v39, v22, v22
	v_fmac_f32_e32 v40, v24, v24
	v_add_f32_e32 v39, v39, v40
	v_add_f32_e32 v38, v38, v39
	v_mul_f32_e32 v39, v19, v19
	v_mul_f32_e32 v40, v21, v21
	v_fmac_f32_e32 v39, v18, v18
	v_fmac_f32_e32 v40, v20, v20
	v_add_f32_e32 v39, v39, v40
	v_add_f32_e32 v38, v38, v39
	v_mov_b32_e32 v39, v38
	s_nop 1
	v_permlane16_swap_b32_e32 v38, v39
	v_add_f32_e32 v38, v38, v39
	v_mov_b32_e32 v39, v38
; __device__ __forceinline__ unsigned cvt_pk_bf16(float lo, float hi) { unsigned r; asm volatile("v_cvt_pk_bf16_f32 %0, %1, %2" : "=v"(r) : "v"(lo), "v"(hi)); return r; }
;     __device__ __forceinline__ void operator()(const f32x4 (&acc)[2][2][4][2], const pg8::Unit& u, int wr, int wc, int fr, int fq) const {
;     ...
;                 for (int m = 0; m < 4; ++m) {
;                     float ss = 0.f;
; #pragma unroll
;                     for (int bj = 0; bj < 2; ++bj)
; #pragma unroll
;                         for (int n = 0; n < 2; ++n) { const f32x4 x = acc[ai][bj][m][n]; ss += (x[0] * x[0] + x[1] * x[1]) + (x[2] * x[2] + x[3] * x[3]); }
;                     ss = row4_sum(ss);
;                     const float r = rsqrtf(ss * (1.f / 64.f) + EPS) * osc;
;                     bf16_t* rowp = base + (size_t)(row0 + ai * 128 + m * 16) * 512 + col0;
; #pragma unroll
;                     for (int bj = 0; bj < 2; ++bj) { const f32x4 v0 = acc[ai][bj][m][0] * r * g[bj][0], v1 = acc[ai][bj][m][1] * r * g[bj][1];
;                         u32x4 w; w.x = cvt_pk_bf16(v0[0], v0[1]); w.y = cvt_pk_bf16(v0[2], v0[3]); w.z = cvt_pk_bf16(v1[0], v1[1]); w.w = cvt_pk_bf16(v1[2], v1[3]);
;                         *(u32x4*)(rowp + 32 * bj) = w; }
;                 }
	s_nop 1
	v_permlane32_swap_b32_e32 v38, v39
	v_add_f32_e32 v38, v38, v39
	v_fmamk_f32 v38, v38, 0x3c800000, v188
	v_mul_f32_e32 v39, 0x4b800000, v38
	v_cmp_gt_f32_e32 vcc, s91, v38
	v_cvt_pk_bf16_f32 v36, v36, v37
	v_cvt_pk_bf16_f32 v37, v42, v43
	v_mov_b32_dpp v212, v200 quad_perm:[1,0,3,2] row_mask:0xf bank_mask:0xf
	v_mov_b32_dpp v213, v201 quad_perm:[1,0,3,2] row_mask:0xf bank_mask:0xf
	v_mov_b32_dpp v214, v202 quad_perm:[1,0,3,2] row_mask:0xf bank_mask:0xf
	v_mov_b32_dpp v215, v203 quad_perm:[1,0,3,2] row_mask:0xf bank_mask:0xf
	v_mov_b32_dpp v204, v34 quad_perm:[1,0,3,2] row_mask:0xf bank_mask:0xf
	v_mov_b32_dpp v205, v35 quad_perm:[1,0,3,2] row_mask:0xf bank_mask:0xf
	v_mov_b32_dpp v206, v36 quad_perm:[1,0,3,2] row_mask:0xf bank_mask:0xf
	v_mov_b32_dpp v207, v37 quad_perm:[1,0,3,2] row_mask:0xf bank_mask:0xf
	v_cndmask_b32_e64 v212, v34, v212, s[4:5]
	v_cndmask_b32_e64 v213, v35, v213, s[4:5]
	v_cndmask_b32_e64 v214, v36, v214, s[4:5]
	v_cndmask_b32_e64 v215, v37, v215, s[4:5]
	v_cndmask_b32_e64 v208, v204, v200, s[4:5]
	v_cndmask_b32_e64 v209, v205, v201, s[4:5]
	v_cndmask_b32_e64 v210, v206, v202, s[4:5]
	v_cndmask_b32_e64 v211, v207, v203, s[4:5]
	global_store_dwordx4 v[216:217], v[208:211], off
	global_store_dwordx4 v[216:217], v[212:215], off offset:1024
	s_nop 0
	v_cndmask_b32_e32 v38, v38, v39, vcc
	v_rsq_f32_e32 v38, v38
	v_lshl_add_u64 v[36:37], v[174:175], 0, s[20:21]
	v_mul_f32_e32 v34, 0x45800000, v38
	v_cndmask_b32_e32 v34, v38, v34, vcc
	v_mul_f32_e32 v34, v178, v34
	v_pk_mul_f32 v[30:31], v[30:31], v[34:35] op_sel_hi:[1,0]
	v_pk_mul_f32 v[26:27], v[26:27], v[34:35] op_sel_hi:[1,0]
	v_pk_mul_f32 v[30:31], v[142:143], v[30:31]
	v_pk_mul_f32 v[28:29], v[28:29], v[34:35] op_sel_hi:[1,0]
	v_pk_mul_f32 v[32:33], v[32:33], v[34:35] op_sel_hi:[1,0]
	v_pk_mul_f32 v[38:39], v[140:141], v[28:29]
	v_pk_mul_f32 v[28:29], v[138:139], v[26:27]
	v_cvt_pk_bf16_f32 v26, v30, v31
	v_add_co_u32_e32 v30, vcc, s89, v174
	v_pk_mul_f32 v[22:23], v[22:23], v[34:35] op_sel_hi:[1,0]
	v_pk_mul_f32 v[32:33], v[144:145], v[32:33]
	v_addc_co_u32_e32 v31, vcc, 0, v175, vcc
	v_cvt_pk_bf16_f32 v27, v32, v33
	v_pk_mul_f32 v[22:23], v[134:135], v[22:23]
	v_pk_mul_f32 v[18:19], v[18:19], v[34:35] op_sel_hi:[1,0]
	v_pk_mul_f32 v[20:21], v[20:21], v[34:35] op_sel_hi:[1,0]
	v_cvt_pk_bf16_f32 v28, v28, v29
	v_cvt_pk_bf16_f32 v29, v38, v39
	v_mov_b32_e32 v200, v26
	v_mov_b32_e32 v201, v27
	v_mov_b32_e32 v202, v28
	v_mov_b32_e32 v203, v29
	v_lshl_add_u64 v[216:217], v[30:31], 0, v[218:219]
	v_pk_mul_f32 v[24:25], v[24:25], v[34:35] op_sel_hi:[1,0]
	s_nop 0
	v_pk_mul_f32 v[26:27], v[132:133], v[20:21]
	v_pk_mul_f32 v[20:21], v[130:131], v[18:19]
	v_cvt_pk_bf16_f32 v18, v22, v23
	v_mul_f32_e32 v22, v15, v15
	v_mul_f32_e32 v23, v17, v17
	v_pk_mul_f32 v[24:25], v[136:137], v[24:25]
	v_fmac_f32_e32 v22, v14, v14
	v_fmac_f32_e32 v23, v16, v16
	v_cvt_pk_bf16_f32 v19, v24, v25
	v_add_f32_e32 v22, v22, v23
	v_mul_f32_e32 v23, v11, v11
	v_mul_f32_e32 v24, v13, v13
	v_fmac_f32_e32 v23, v10, v10
	v_fmac_f32_e32 v24, v12, v12
	v_add_f32_e32 v23, v23, v24
	v_add_f32_e32 v22, v22, v23
	v_mul_f32_e32 v23, v7, v7
	v_mul_f32_e32 v24, v9, v9
	v_fmac_f32_e32 v23, v6, v6
	v_fmac_f32_e32 v24, v8, v8
	v_add_f32_e32 v23, v23, v24
	v_add_f32_e32 v22, v22, v23
	v_mul_f32_e32 v23, v3, v3
	v_mul_f32_e32 v24, v5, v5
	v_fmac_f32_e32 v23, v2, v2
	v_fmac_f32_e32 v24, v4, v4
	v_add_f32_e32 v23, v23, v24
	v_add_f32_e32 v22, v22, v23
	v_mov_b32_e32 v23, v22
	s_nop 1
	v_permlane16_swap_b32_e32 v22, v23
	v_add_f32_e32 v22, v22, v23
	v_mov_b32_e32 v23, v22
	s_nop 1
	v_permlane32_swap_b32_e32 v22, v23
	v_add_f32_e32 v22, v22, v23
	v_fmamk_f32 v22, v22, 0x3c800000, v188
	v_mul_f32_e32 v23, 0x4b800000, v22
	v_cmp_gt_f32_e32 vcc, s91, v22
; __device__ __forceinline__ unsigned cvt_pk_bf16(float lo, float hi) { unsigned r; asm volatile("v_cvt_pk_bf16_f32 %0, %1, %2" : "=v"(r) : "v"(lo), "v"(hi)); return r; }
; template <class Epi, class Sched, bool ALIGN_EPI = false, bool SP2 = false>
; __device__ __forceinline__ void gemm_phase(PG8_LAS unsigned char* lds, const Gemm g, const Sched& S, const Epi& E) {
;     ...
;         if (!has_next) break;
;     __device__ __forceinline__ void operator()(const f32x4 (&acc)[2][2][4][2], const pg8::Unit& u, int wr, int wc, int fr, int fq) const {
;     ...
;                 for (int m = 0; m < 4; ++m) {
;                     float ss = 0.f;
; #pragma unroll
;                     for (int bj = 0; bj < 2; ++bj)
; #pragma unroll
;                         for (int n = 0; n < 2; ++n) { const f32x4 x = acc[ai][bj][m][n]; ss += (x[0] * x[0] + x[1] * x[1]) + (x[2] * x[2] + x[3] * x[3]); }
;                     ss = row4_sum(ss);
;                     const float r = rsqrtf(ss * (1.f / 64.f) + EPS) * osc;
;                     bf16_t* rowp = base + (size_t)(row0 + ai * 128 + m * 16) * 512 + col0;
; #pragma unroll
;                     for (int bj = 0; bj < 2; ++bj) { const f32x4 v0 = acc[ai][bj][m][0] * r * g[bj][0], v1 = acc[ai][bj][m][1] * r * g[bj][1];
;                         u32x4 w; w.x = cvt_pk_bf16(v0[0], v0[1]); w.y = cvt_pk_bf16(v0[2], v0[3]); w.z = cvt_pk_bf16(v1[0], v1[1]); w.w = cvt_pk_bf16(v1[2], v1[3]);
;                         *(u32x4*)(rowp + 32 * bj) = w; }
;                 }
	v_cvt_pk_bf16_f32 v20, v20, v21
	v_cvt_pk_bf16_f32 v21, v26, v27
	v_mov_b32_dpp v212, v200 quad_perm:[1,0,3,2] row_mask:0xf bank_mask:0xf
	v_mov_b32_dpp v213, v201 quad_perm:[1,0,3,2] row_mask:0xf bank_mask:0xf
	v_mov_b32_dpp v214, v202 quad_perm:[1,0,3,2] row_mask:0xf bank_mask:0xf
	v_mov_b32_dpp v215, v203 quad_perm:[1,0,3,2] row_mask:0xf bank_mask:0xf
	v_mov_b32_dpp v204, v18 quad_perm:[1,0,3,2] row_mask:0xf bank_mask:0xf
	v_mov_b32_dpp v205, v19 quad_perm:[1,0,3,2] row_mask:0xf bank_mask:0xf
	v_mov_b32_dpp v206, v20 quad_perm:[1,0,3,2] row_mask:0xf bank_mask:0xf
	v_mov_b32_dpp v207, v21 quad_perm:[1,0,3,2] row_mask:0xf bank_mask:0xf
	v_cndmask_b32_e64 v212, v18, v212, s[4:5]
	v_cndmask_b32_e64 v213, v19, v213, s[4:5]
	v_cndmask_b32_e64 v214, v20, v214, s[4:5]
	v_cndmask_b32_e64 v215, v21, v215, s[4:5]
	v_cndmask_b32_e64 v208, v204, v200, s[4:5]
	v_cndmask_b32_e64 v209, v205, v201, s[4:5]
	v_cndmask_b32_e64 v210, v206, v202, s[4:5]
	v_cndmask_b32_e64 v211, v207, v203, s[4:5]
	global_store_dwordx4 v[216:217], v[208:211], off
	global_store_dwordx4 v[216:217], v[212:215], off offset:1024
	s_nop 0
	v_cndmask_b32_e32 v22, v22, v23, vcc
	v_rsq_f32_e32 v22, v22
	v_lshl_add_u64 v[20:21], v[174:175], 0, s[24:25]
	v_mul_f32_e32 v18, 0x45800000, v22
	v_cndmask_b32_e32 v18, v22, v18, vcc
	v_mul_f32_e32 v18, v178, v18
	v_pk_mul_f32 v[14:15], v[14:15], v[18:19] op_sel_hi:[1,0]
	v_pk_mul_f32 v[10:11], v[10:11], v[18:19] op_sel_hi:[1,0]
	v_pk_mul_f32 v[14:15], v[142:143], v[14:15]
	v_pk_mul_f32 v[12:13], v[12:13], v[18:19] op_sel_hi:[1,0]
	v_pk_mul_f32 v[16:17], v[16:17], v[18:19] op_sel_hi:[1,0]
	v_pk_mul_f32 v[22:23], v[140:141], v[12:13]
	v_pk_mul_f32 v[12:13], v[138:139], v[10:11]
	v_cvt_pk_bf16_f32 v10, v14, v15
	v_add_co_u32_e32 v14, vcc, s90, v174
	v_pk_mul_f32 v[16:17], v[144:145], v[16:17]
	s_nop 0
	v_addc_co_u32_e32 v15, vcc, 0, v175, vcc
	v_cvt_pk_bf16_f32 v11, v16, v17
	v_pk_mul_f32 v[2:3], v[2:3], v[18:19] op_sel_hi:[1,0]
	v_pk_mul_f32 v[4:5], v[4:5], v[18:19] op_sel_hi:[1,0]
	v_cvt_pk_bf16_f32 v12, v12, v13
	v_cvt_pk_bf16_f32 v13, v22, v23
	v_mov_b32_e32 v200, v10
	v_mov_b32_e32 v201, v11
	v_mov_b32_e32 v202, v12
	v_mov_b32_e32 v203, v13
	v_lshl_add_u64 v[216:217], v[14:15], 0, v[218:219]
	v_pk_mul_f32 v[6:7], v[6:7], v[18:19] op_sel_hi:[1,0]
	v_pk_mul_f32 v[8:9], v[8:9], v[18:19] op_sel_hi:[1,0]
	v_pk_mul_f32 v[10:11], v[132:133], v[4:5]
	v_pk_mul_f32 v[4:5], v[130:131], v[2:3]
	v_pk_mul_f32 v[8:9], v[136:137], v[8:9]
	v_pk_mul_f32 v[6:7], v[134:135], v[6:7]
	s_nop 0
	v_cvt_pk_bf16_f32 v2, v6, v7
	v_cvt_pk_bf16_f32 v3, v8, v9
	v_cvt_pk_bf16_f32 v4, v4, v5
	v_cvt_pk_bf16_f32 v5, v10, v11
	v_mov_b32_dpp v212, v200 quad_perm:[1,0,3,2] row_mask:0xf bank_mask:0xf
	v_mov_b32_dpp v213, v201 quad_perm:[1,0,3,2] row_mask:0xf bank_mask:0xf
	v_mov_b32_dpp v214, v202 quad_perm:[1,0,3,2] row_mask:0xf bank_mask:0xf
	v_mov_b32_dpp v215, v203 quad_perm:[1,0,3,2] row_mask:0xf bank_mask:0xf
	v_mov_b32_dpp v204, v2 quad_perm:[1,0,3,2] row_mask:0xf bank_mask:0xf
	v_mov_b32_dpp v205, v3 quad_perm:[1,0,3,2] row_mask:0xf bank_mask:0xf
	v_mov_b32_dpp v206, v4 quad_perm:[1,0,3,2] row_mask:0xf bank_mask:0xf
	v_mov_b32_dpp v207, v5 quad_perm:[1,0,3,2] row_mask:0xf bank_mask:0xf
	v_cndmask_b32_e64 v212, v2, v212, s[4:5]
	v_cndmask_b32_e64 v213, v3, v213, s[4:5]
	v_cndmask_b32_e64 v214, v4, v214, s[4:5]
	v_cndmask_b32_e64 v215, v5, v215, s[4:5]
	v_cndmask_b32_e64 v208, v204, v200, s[4:5]
	v_cndmask_b32_e64 v209, v205, v201, s[4:5]
	v_cndmask_b32_e64 v210, v206, v202, s[4:5]
	v_cndmask_b32_e64 v211, v207, v203, s[4:5]
	global_store_dwordx4 v[216:217], v[208:211], off
	global_store_dwordx4 v[216:217], v[212:215], off offset:1024
	s_andn2_b64 vcc, exec, s[0:1]
	s_mov_b64 s[0:1], -1
	s_cbranch_vccnz .LBB0_158
